# P3b: 16 output-gate loads issued after the v-tile staging loads (staging waits vmcnt 23..16), consumed in the epilogue behind a counted wait
# baseline (speedup 1.0000x reference)
; DI unsigned pk2(float lo, float hi) { f32x2 v = {lo, hi}; bf16x2_t b = __builtin_convertvector(v, bf16x2_t); return __builtin_bit_cast(unsigned, b); }
; DI float bflo(unsigned w) { return __uint_as_float(w << 16); }
; DI float bfhi(unsigned w) { return __uint_as_float(w & 0xffff0000u); }
; DI void gla_out_unit(int chunk, const Params& p, LAS unsigned char* lds) {
;     ...
;     float ss = 0.f;
; #pragma unroll
;     for (int vb = 0; vb < 4; ++vb)
; #pragma unroll
;         for (int e = 0; e < 16; ++e) ss += oT[vb][e] * oT[vb][e];
;     ss += __shfl_xor(ss, 32);
;     const float rstd = rsqrtf(ss * (1.0f / 128.0f) + EPS);
;     bf16_t* mix = (bf16_t*)(p.ws + WS_MIX);
; #pragma unroll
;     for (int vb = 0; vb < 4; ++vb)
; #pragma unroll
;         for (int g = 0; g < 4; ++g) { const int v0 = 32 * vb + 8 * g + 4 * hi;
;             const u32x2 gw = gwv[vb][g];
;             const f32x4 gn = *(const f32x4*)(p.gla_og + h * 128 + v0);
;             float r[4] = {bflo(gw.x), bfhi(gw.x), bflo(gw.y), bfhi(gw.y)}; float ov[4];
; #pragma unroll
;             for (int e = 0; e < 4; ++e) { const float sg = r[e] / (1.0f + __expf(-r[e])); ov[e] = oT[vb][4 * g + e] * rstd * gn[e] * sg; }
;             u32x2 w; w.x = pk2(ov[0], ov[1]); w.y = pk2(ov[2], ov[3]);
;             *(u32x2*)(mix + (size_t)tok * DM + 512 + h * 128 + v0) = w; }
.LBB0_617:
	s_nop 1
	v_mul_f32_e32 v74, v49, v49
	v_fmac_f32_e32 v74, v48, v48
	v_fmac_f32_e32 v74, v50, v50
	v_fmac_f32_e32 v74, v51, v51
	v_fmac_f32_e32 v74, v52, v52
	v_fmac_f32_e32 v74, v53, v53
	v_fmac_f32_e32 v74, v54, v54
	v_fmac_f32_e32 v74, v55, v55
	v_fmac_f32_e32 v74, v56, v56
	v_fmac_f32_e32 v74, v57, v57
	v_fmac_f32_e32 v74, v58, v58
	v_fmac_f32_e32 v74, v59, v59
	v_fmac_f32_e32 v74, v60, v60
	v_fmac_f32_e32 v74, v61, v61
	v_fmac_f32_e32 v74, v62, v62
	v_fmac_f32_e32 v74, v63, v63
	v_fmac_f32_e32 v74, v32, v32
	v_fmac_f32_e32 v74, v33, v33
	v_fmac_f32_e32 v74, v34, v34
	v_fmac_f32_e32 v74, v35, v35
	v_fmac_f32_e32 v74, v36, v36
	v_fmac_f32_e32 v74, v37, v37
	v_fmac_f32_e32 v74, v38, v38
	v_fmac_f32_e32 v74, v39, v39
	v_fmac_f32_e32 v74, v40, v40
	v_fmac_f32_e32 v74, v41, v41
	v_fmac_f32_e32 v74, v42, v42
	v_fmac_f32_e32 v74, v43, v43
	v_fmac_f32_e32 v74, v44, v44
	v_fmac_f32_e32 v74, v45, v45
	v_fmac_f32_e32 v74, v46, v46
	v_fmac_f32_e32 v74, v47, v47
	v_fmac_f32_e32 v74, v16, v16
	v_fmac_f32_e32 v74, v17, v17
	v_fmac_f32_e32 v74, v18, v18
	v_fmac_f32_e32 v74, v19, v19
	v_fmac_f32_e32 v74, v20, v20
	v_fmac_f32_e32 v74, v21, v21
	v_fmac_f32_e32 v74, v22, v22
	v_fmac_f32_e32 v74, v23, v23
	v_fmac_f32_e32 v74, v24, v24
	v_fmac_f32_e32 v74, v25, v25
	v_fmac_f32_e32 v74, v26, v26
	v_fmac_f32_e32 v74, v27, v27
	v_fmac_f32_e32 v74, v28, v28
	v_fmac_f32_e32 v74, v29, v29
	v_fmac_f32_e32 v74, v30, v30
	v_fmac_f32_e32 v74, v31, v31
	v_fmac_f32_e32 v74, v0, v0
	v_fmac_f32_e32 v74, v1, v1
	v_fmac_f32_e32 v74, v2, v2
	v_fmac_f32_e32 v74, v3, v3
	v_fmac_f32_e32 v74, v4, v4
	v_fmac_f32_e32 v74, v5, v5
	v_pk_mul_f32 v[72:73], v[6:7], v[6:7]
	v_pk_mul_f32 v[70:71], v[8:9], v[8:9]
	v_add_f32_e32 v72, v72, v74
	v_add_f32_e32 v72, v73, v72
	v_add_f32_e32 v70, v70, v72
	v_pk_mul_f32 v[68:69], v[10:11], v[10:11]
	v_add_f32_e32 v70, v71, v70
	v_add_f32_e32 v68, v68, v70
	v_pk_mul_f32 v[66:67], v[12:13], v[12:13]
	v_add_f32_e32 v68, v69, v68
	v_add_f32_e32 v66, v66, v68
	v_pk_mul_f32 v[64:65], v[14:15], v[14:15]
	v_add_f32_e32 v66, v67, v66
	v_add_f32_e32 v64, v64, v66
	v_add_f32_e32 v64, v65, v64
	ds_bpermute_b32 v65, v210, v64
	s_mov_b32 s8, 0x800000
	v_readlane_b32 s36, v254, 0
	v_ashrrev_i32_e32 v199, 31, v198
	v_readlane_b32 s38, v254, 2
	s_waitcnt lgkmcnt(0)
	v_add_f32_e32 v64, v64, v65
	v_fmamk_f32 v64, v64, 0x3c000000, v211
	v_cmp_gt_f32_e32 vcc, s8, v64
	v_mul_f32_e32 v65, 0x4b800000, v64
	v_readlane_b32 s39, v254, 3
	v_cndmask_b32_e32 v64, v64, v65, vcc
	v_rsq_f32_e32 v64, v64
	s_lshl_b64 s[8:9], s[22:23], 2
	s_mov_b64 s[18:19], s[38:39]
	s_add_u32 s20, s18, s8
	v_mul_f32_e32 v65, 0x45800000, v64
	v_cndmask_b32_e32 v68, v64, v65, vcc
	v_lshlrev_b64 v[64:65], 11, v[198:199]
	v_lshl_add_u64 v[64:65], s[76:77], 0, v[64:65]
	s_addc_u32 s21, s19, s9
	v_lshl_add_u64 v[64:65], s[22:23], 1, v[64:65]
	s_mov_b64 s[8:9], 0x16000400
	v_lshlrev_b32_e32 v69, 2, v203
	v_lshl_add_u64 v[70:71], v[64:65], 0, s[8:9]
	global_load_dwordx4 v[84:87], v69, s[20:21]
	global_load_dwordx4 v[88:91], v69, s[20:21] offset:32
	global_load_dwordx4 v[92:95], v69, s[20:21] offset:64
	global_load_dwordx4 v[96:99], v69, s[20:21] offset:96
	global_load_dwordx4 v[100:103], v69, s[20:21] offset:128
	global_load_dwordx4 v[104:107], v69, s[20:21] offset:160
	global_load_dwordx4 v[108:111], v69, s[20:21] offset:192
	global_load_dwordx4 v[112:115], v69, s[20:21] offset:224
	global_load_dwordx4 v[116:119], v69, s[20:21] offset:256
	global_load_dwordx4 v[120:123], v69, s[20:21] offset:288
	global_load_dwordx4 v[124:127], v69, s[20:21] offset:320
	global_load_dwordx4 v[128:131], v69, s[20:21] offset:352
	global_load_dwordx4 v[132:135], v69, s[20:21] offset:384
	global_load_dwordx4 v[136:139], v69, s[20:21] offset:416
	global_load_dwordx4 v[140:143], v69, s[20:21] offset:448
	global_load_dwordx4 v[144:147], v69, s[20:21] offset:480
	s_waitcnt vmcnt(16)
	v_lshlrev_b32_e32 v74, 16, v200
	v_and_b32_e32 v75, 0xffff0000, v200
	v_mul_f32_e32 v72, 0xbfb8aa3b, v74
	v_mul_f32_e32 v73, 0xbfb8aa3b, v75
	v_exp_f32_e32 v72, v72
	v_exp_f32_e32 v73, v73
	v_pk_mul_f32 v[48:49], v[48:49], v[68:69] op_sel_hi:[1,0]
	v_pk_mul_f32 v[50:51], v[50:51], v[68:69] op_sel_hi:[1,0]
	v_lshlrev_b32_e32 v166, 1, v203
	v_pk_add_f32 v[72:73], v[72:73], 1.0 op_sel_hi:[1,0]
	v_mov_b32_e32 v207, v167
	v_div_scale_f32 v76, s[8:9], v73, v73, v75
	v_rcp_f32_e32 v77, v76
	v_pk_mul_f32 v[52:53], v[52:53], v[68:69] op_sel_hi:[1,0]
	v_pk_mul_f32 v[54:55], v[54:55], v[68:69] op_sel_hi:[1,0]
	v_mov_b32_e32 v205, v167
	v_fma_f32 v78, -v76, v77, 1.0
	v_fmac_f32_e32 v77, v78, v77
	v_div_scale_f32 v78, vcc, v75, v73, v75
	v_mul_f32_e32 v79, v78, v77
	v_fma_f32 v80, -v76, v79, v78
	v_fmac_f32_e32 v79, v80, v77
	v_fma_f32 v76, -v76, v79, v78
	v_div_fmas_f32 v76, v76, v77, v79
	v_div_fixup_f32 v73, v76, v73, v75
	v_div_scale_f32 v75, s[8:9], v72, v72, v74
	v_rcp_f32_e32 v76, v75
	v_pk_mul_f32 v[56:57], v[56:57], v[68:69] op_sel_hi:[1,0]
	v_mov_b32_e32 v203, v167
	v_pk_mul_f32 v[32:33], v[32:33], v[68:69] op_sel_hi:[1,0]
	v_fma_f32 v77, -v75, v76, 1.0
	v_fmac_f32_e32 v76, v77, v76
	v_div_scale_f32 v77, vcc, v74, v72, v74
	v_mul_f32_e32 v78, v77, v76
	v_fma_f32 v79, -v75, v78, v77
	v_fmac_f32_e32 v78, v79, v76
	v_fma_f32 v75, -v75, v78, v77
	v_div_fmas_f32 v75, v75, v76, v78
	v_div_fixup_f32 v72, v75, v72, v74
	v_pk_mul_f32 v[34:35], v[34:35], v[68:69] op_sel_hi:[1,0]
	v_pk_mul_f32 v[36:37], v[36:37], v[68:69] op_sel_hi:[1,0]
	v_pk_mul_f32 v[38:39], v[38:39], v[68:69] op_sel_hi:[1,0]
	v_pk_mul_f32 v[16:17], v[16:17], v[68:69] op_sel_hi:[1,0]
	v_pk_mul_f32 v[18:19], v[18:19], v[68:69] op_sel_hi:[1,0]
	v_pk_mul_f32 v[20:21], v[20:21], v[68:69] op_sel_hi:[1,0]
	v_pk_mul_f32 v[22:23], v[22:23], v[68:69] op_sel_hi:[1,0]
	v_pk_mul_f32 v[0:1], v[0:1], v[68:69] op_sel_hi:[1,0]
	v_pk_mul_f32 v[2:3], v[2:3], v[68:69] op_sel_hi:[1,0]
	v_pk_mul_f32 v[4:5], v[4:5], v[68:69] op_sel_hi:[1,0]
	v_pk_mul_f32 v[6:7], v[6:7], v[68:69] op_sel_hi:[1,0]
	s_add_i32 s12, s12, s92
	s_add_i32 s0, s0, s33
	s_add_i32 s1, s1, s4
	s_cmpk_gt_i32 s12, 0x1ff
	v_readlane_b32 s37, v254, 1
	v_readlane_b32 s40, v254, 4
	v_readlane_b32 s41, v254, 5
	v_readlane_b32 s42, v254, 6
	v_readlane_b32 s43, v254, 7
	v_readlane_b32 s44, v254, 8
	v_readlane_b32 s45, v254, 9
	v_readlane_b32 s46, v254, 10
	v_readlane_b32 s47, v254, 11
	v_readlane_b32 s48, v254, 12
	v_readlane_b32 s49, v254, 13
	v_readlane_b32 s50, v254, 14
	v_readlane_b32 s51, v254, 15
	s_waitcnt vmcnt(15)
; DI unsigned pk2(float lo, float hi) { f32x2 v = {lo, hi}; bf16x2_t b = __builtin_convertvector(v, bf16x2_t); return __builtin_bit_cast(unsigned, b); }
; DI float bflo(unsigned w) { return __uint_as_float(w << 16); }
; DI float bfhi(unsigned w) { return __uint_as_float(w & 0xffff0000u); }
; DI void gla_out_unit(int chunk, const Params& p, LAS unsigned char* lds) {
;     ...
;         for (int g = 0; g < 4; ++g) { const int v0 = 32 * vb + 8 * g + 4 * hi;
;             const u32x2 gw = gwv[vb][g];
;             const f32x4 gn = *(const f32x4*)(p.gla_og + h * 128 + v0);
;             float r[4] = {bflo(gw.x), bfhi(gw.x), bflo(gw.y), bfhi(gw.y)}; float ov[4];
; #pragma unroll
;             for (int e = 0; e < 4; ++e) { const float sg = r[e] / (1.0f + __expf(-r[e])); ov[e] = oT[vb][4 * g + e] * rstd * gn[e] * sg; }
;             u32x2 w; w.x = pk2(ov[0], ov[1]); w.y = pk2(ov[2], ov[3]);
;             *(u32x2*)(mix + (size_t)tok * DM + 512 + h * 128 + v0) = w; }
	v_pk_mul_f32 v[48:49], v[84:85], v[48:49]
	s_nop 0
	v_pk_mul_f32 v[48:49], v[72:73], v[48:49]
	v_lshlrev_b32_e32 v72, 16, v201
	v_and_b32_e32 v73, 0xffff0000, v201
	v_mul_f32_e32 v64, 0xbfb8aa3b, v72
	v_mul_f32_e32 v65, 0xbfb8aa3b, v73
	v_exp_f32_e32 v64, v64
	v_exp_f32_e32 v65, v65
	v_pk_mul_f32 v[50:51], v[86:87], v[50:51]
	v_pk_add_f32 v[64:65], v[64:65], 1.0 op_sel_hi:[1,0]
	s_nop 0
	v_div_scale_f32 v74, s[8:9], v65, v65, v73
	v_rcp_f32_e32 v75, v74
	s_nop 0
	v_fma_f32 v76, -v74, v75, 1.0
	v_fmac_f32_e32 v75, v76, v75
	v_div_scale_f32 v76, vcc, v73, v65, v73
	v_mul_f32_e32 v77, v76, v75
	v_fma_f32 v78, -v74, v77, v76
	v_fmac_f32_e32 v77, v78, v75
	v_fma_f32 v74, -v74, v77, v76
	v_div_fmas_f32 v74, v74, v75, v77
	v_div_fixup_f32 v65, v74, v65, v73
	v_div_scale_f32 v73, s[8:9], v64, v64, v72
	v_rcp_f32_e32 v74, v73
	s_nop 0
	v_fma_f32 v75, -v73, v74, 1.0
	v_fmac_f32_e32 v74, v75, v74
	v_div_scale_f32 v75, vcc, v72, v64, v72
	v_mul_f32_e32 v76, v75, v74
	v_fma_f32 v77, -v73, v76, v75
	v_fmac_f32_e32 v76, v77, v74
	v_fma_f32 v73, -v73, v76, v75
	v_div_fmas_f32 v73, v73, v74, v76
	v_div_fixup_f32 v64, v73, v64, v72
	v_pk_mul_f32 v[50:51], v[64:65], v[50:51]
	v_cvt_pk_bf16_f32 v64, v48, v49
	v_cvt_pk_bf16_f32 v65, v50, v51
	v_lshl_add_u64 v[48:49], v[70:71], 0, v[166:167]
	global_store_dwordx2 v[48:49], v[64:65], off
	v_lshl_add_u64 v[50:51], v[206:207], 2, s[20:21]
	v_lshlrev_b32_e32 v72, 16, v196
	v_and_b32_e32 v73, 0xffff0000, v196
	v_mul_f32_e32 v50, 0xbfb8aa3b, v72
	v_mul_f32_e32 v51, 0xbfb8aa3b, v73
	v_exp_f32_e32 v50, v50
	v_exp_f32_e32 v51, v51
	s_waitcnt vmcnt(15)
	v_pk_mul_f32 v[52:53], v[88:89], v[52:53]
	v_pk_add_f32 v[50:51], v[50:51], 1.0 op_sel_hi:[1,0]
	v_lshlrev_b32_e32 v64, 16, v197
	v_div_scale_f32 v74, s[8:9], v51, v51, v73
	v_rcp_f32_e32 v75, v74
	v_and_b32_e32 v65, 0xffff0000, v197
	v_pk_mul_f32 v[54:55], v[90:91], v[54:55]
	v_fma_f32 v76, -v74, v75, 1.0
	v_fmac_f32_e32 v75, v76, v75
	v_div_scale_f32 v76, vcc, v73, v51, v73
	v_mul_f32_e32 v77, v76, v75
	v_fma_f32 v78, -v74, v77, v76
	v_fmac_f32_e32 v77, v78, v75
	v_fma_f32 v74, -v74, v77, v76
	v_div_fmas_f32 v74, v74, v75, v77
	v_div_fixup_f32 v51, v74, v51, v73
	v_div_scale_f32 v73, s[8:9], v50, v50, v72
	v_rcp_f32_e32 v74, v73
	s_nop 0
	v_fma_f32 v75, -v73, v74, 1.0
	v_fmac_f32_e32 v74, v75, v74
	v_div_scale_f32 v75, vcc, v72, v50, v72
	v_mul_f32_e32 v76, v75, v74
	v_fma_f32 v77, -v73, v76, v75
	v_fmac_f32_e32 v76, v77, v74
	v_fma_f32 v73, -v73, v76, v75
	v_div_fmas_f32 v73, v73, v74, v76
	v_div_fixup_f32 v50, v73, v50, v72
	v_pk_mul_f32 v[50:51], v[50:51], v[52:53]
	v_mul_f32_e32 v52, 0xbfb8aa3b, v64
	v_mul_f32_e32 v53, 0xbfb8aa3b, v65
	v_exp_f32_e32 v52, v52
	v_exp_f32_e32 v53, v53
	v_cvt_pk_bf16_f32 v50, v50, v51
	v_pk_add_f32 v[52:53], v[52:53], 1.0 op_sel_hi:[1,0]
	s_nop 0
	v_div_scale_f32 v72, s[8:9], v53, v53, v65
	v_rcp_f32_e32 v73, v72
	s_nop 0
	v_fma_f32 v74, -v72, v73, 1.0
	v_fmac_f32_e32 v73, v74, v73
	v_div_scale_f32 v74, vcc, v65, v53, v65
	v_mul_f32_e32 v75, v74, v73
	v_fma_f32 v76, -v72, v75, v74
	v_fmac_f32_e32 v75, v76, v73
	v_fma_f32 v72, -v72, v75, v74
	v_div_fmas_f32 v72, v72, v73, v75
	v_div_fixup_f32 v53, v72, v53, v65
	v_div_scale_f32 v65, s[8:9], v52, v52, v64
	v_rcp_f32_e32 v72, v65
	s_nop 0
	v_fma_f32 v73, -v65, v72, 1.0
	v_fmac_f32_e32 v72, v73, v72
	v_div_scale_f32 v73, vcc, v64, v52, v64
	v_mul_f32_e32 v74, v73, v72
	v_fma_f32 v75, -v65, v74, v73
	v_fmac_f32_e32 v74, v75, v72
	v_fma_f32 v65, -v65, v74, v73
	v_div_fmas_f32 v65, v65, v72, v74
	v_div_fixup_f32 v52, v65, v52, v64
	v_pk_mul_f32 v[52:53], v[52:53], v[54:55]
	v_lshlrev_b32_e32 v64, 16, v194
	v_cvt_pk_bf16_f32 v51, v52, v53
	v_lshl_add_u64 v[52:53], v[206:207], 1, v[70:71]
	global_store_dwordx2 v[52:53], v[50:51], off
	v_lshl_add_u64 v[50:51], v[204:205], 2, s[20:21]
	v_and_b32_e32 v65, 0xffff0000, v194
	v_mul_f32_e32 v54, 0xbfb8aa3b, v64
	v_mul_f32_e32 v55, 0xbfb8aa3b, v65
	v_exp_f32_e32 v54, v54
	v_exp_f32_e32 v55, v55
	s_waitcnt vmcnt(15)
	v_pk_mul_f32 v[50:51], v[92:93], v[56:57]
	v_pk_add_f32 v[54:55], v[54:55], 1.0 op_sel_hi:[1,0]
	v_lshlrev_b32_e32 v56, 16, v195
	v_div_scale_f32 v66, s[8:9], v55, v55, v65
	v_rcp_f32_e32 v67, v66
	v_and_b32_e32 v57, 0xffff0000, v195
	v_fma_f32 v72, -v66, v67, 1.0
	v_fmac_f32_e32 v67, v72, v67
	v_div_scale_f32 v72, vcc, v65, v55, v65
	v_mul_f32_e32 v73, v72, v67
	v_fma_f32 v74, -v66, v73, v72
	v_fmac_f32_e32 v73, v74, v67
	v_fma_f32 v66, -v66, v73, v72
	v_div_fmas_f32 v66, v66, v67, v73
	v_div_fixup_f32 v55, v66, v55, v65
	v_div_scale_f32 v65, s[8:9], v54, v54, v64
	v_rcp_f32_e32 v66, v65
	s_nop 0
	v_fma_f32 v67, -v65, v66, 1.0
	v_fmac_f32_e32 v66, v67, v66
	v_div_scale_f32 v67, vcc, v64, v54, v64
	v_mul_f32_e32 v72, v67, v66
	v_fma_f32 v73, -v65, v72, v67
	v_fmac_f32_e32 v72, v73, v66
	v_fma_f32 v65, -v65, v72, v67
	v_div_fmas_f32 v65, v65, v66, v72
	v_div_fixup_f32 v54, v65, v54, v64
	v_pk_mul_f32 v[50:51], v[54:55], v[50:51]
	v_mul_f32_e32 v54, 0xbfb8aa3b, v56
	v_mul_f32_e32 v55, 0xbfb8aa3b, v57
	v_exp_f32_e32 v54, v54
	v_exp_f32_e32 v55, v55
	v_cvt_pk_bf16_f32 v50, v50, v51
	v_pk_add_f32 v[54:55], v[54:55], 1.0 op_sel_hi:[1,0]
	s_nop 0
	v_div_scale_f32 v64, s[8:9], v55, v55, v57
	v_rcp_f32_e32 v65, v64
	s_nop 0
	v_fma_f32 v66, -v64, v65, 1.0
	v_fmac_f32_e32 v65, v66, v65
	v_div_scale_f32 v66, vcc, v57, v55, v57
	v_mul_f32_e32 v67, v66, v65
	v_fma_f32 v72, -v64, v67, v66
	v_fmac_f32_e32 v67, v72, v65
	v_fma_f32 v64, -v64, v67, v66
	v_div_fmas_f32 v64, v64, v65, v67
	v_div_fixup_f32 v55, v64, v55, v57
	v_div_scale_f32 v57, s[8:9], v54, v54, v56
	v_rcp_f32_e32 v64, v57
	s_nop 0
	v_fma_f32 v65, -v57, v64, 1.0
	v_fmac_f32_e32 v64, v65, v64
; DI unsigned pk2(float lo, float hi) { f32x2 v = {lo, hi}; bf16x2_t b = __builtin_convertvector(v, bf16x2_t); return __builtin_bit_cast(unsigned, b); }
; DI float bflo(unsigned w) { return __uint_as_float(w << 16); }
; DI float bfhi(unsigned w) { return __uint_as_float(w & 0xffff0000u); }
; DI void gla_out_unit(int chunk, const Params& p, LAS unsigned char* lds) {
;     ...
;         for (int g = 0; g < 4; ++g) { const int v0 = 32 * vb + 8 * g + 4 * hi;
;             const u32x2 gw = gwv[vb][g];
;             const f32x4 gn = *(const f32x4*)(p.gla_og + h * 128 + v0);
;             float r[4] = {bflo(gw.x), bfhi(gw.x), bflo(gw.y), bfhi(gw.y)}; float ov[4];
; #pragma unroll
;             for (int e = 0; e < 4; ++e) { const float sg = r[e] / (1.0f + __expf(-r[e])); ov[e] = oT[vb][4 * g + e] * rstd * gn[e] * sg; }
;             u32x2 w; w.x = pk2(ov[0], ov[1]); w.y = pk2(ov[2], ov[3]);
;             *(u32x2*)(mix + (size_t)tok * DM + 512 + h * 128 + v0) = w; }
	v_div_scale_f32 v65, vcc, v56, v54, v56
	v_mul_f32_e32 v66, v65, v64
	v_fma_f32 v67, -v57, v66, v65
	v_fmac_f32_e32 v66, v67, v64
	v_fma_f32 v57, -v57, v66, v65
	v_div_fmas_f32 v57, v57, v64, v66
	v_div_fixup_f32 v54, v57, v54, v56
	v_pk_mul_f32 v[56:57], v[58:59], v[68:69] op_sel_hi:[1,0]
	s_nop 0
	v_pk_mul_f32 v[52:53], v[94:95], v[56:57]
	v_lshlrev_b32_e32 v56, 16, v192
	v_pk_mul_f32 v[52:53], v[54:55], v[52:53]
	v_and_b32_e32 v57, 0xffff0000, v192
	v_cvt_pk_bf16_f32 v51, v52, v53
	v_lshl_add_u64 v[52:53], v[204:205], 1, v[70:71]
	global_store_dwordx2 v[52:53], v[50:51], off
	v_lshl_add_u64 v[50:51], v[202:203], 2, s[20:21]
	v_mul_f32_e32 v54, 0xbfb8aa3b, v56
	v_mul_f32_e32 v55, 0xbfb8aa3b, v57
	v_exp_f32_e32 v54, v54
	v_exp_f32_e32 v55, v55
	s_nop 0
	v_pk_add_f32 v[54:55], v[54:55], 1.0 op_sel_hi:[1,0]
	s_nop 0
	v_div_scale_f32 v58, s[8:9], v55, v55, v57
	v_rcp_f32_e32 v59, v58
	s_nop 0
	v_fma_f32 v64, -v58, v59, 1.0
	v_fmac_f32_e32 v59, v64, v59
	v_div_scale_f32 v64, vcc, v57, v55, v57
	v_mul_f32_e32 v65, v64, v59
	v_fma_f32 v66, -v58, v65, v64
	v_fmac_f32_e32 v65, v66, v59
	v_fma_f32 v58, -v58, v65, v64
	v_div_fmas_f32 v58, v58, v59, v65
	v_div_fixup_f32 v55, v58, v55, v57
	v_div_scale_f32 v57, s[8:9], v54, v54, v56
	v_rcp_f32_e32 v58, v57
	s_nop 0
	v_fma_f32 v59, -v57, v58, 1.0
	v_fmac_f32_e32 v58, v59, v58
	v_div_scale_f32 v59, vcc, v56, v54, v56
	v_mul_f32_e32 v64, v59, v58
	v_fma_f32 v65, -v57, v64, v59
	v_fmac_f32_e32 v64, v65, v58
	v_fma_f32 v57, -v57, v64, v59
	v_div_fmas_f32 v57, v57, v58, v64
	v_div_fixup_f32 v54, v57, v54, v56
	v_pk_mul_f32 v[56:57], v[60:61], v[68:69] op_sel_hi:[1,0]
	s_waitcnt vmcnt(15)
	v_pk_mul_f32 v[50:51], v[96:97], v[56:57]
	v_lshlrev_b32_e32 v56, 16, v193
	v_and_b32_e32 v57, 0xffff0000, v193
	v_pk_mul_f32 v[50:51], v[54:55], v[50:51]
	v_mul_f32_e32 v54, 0xbfb8aa3b, v56
	v_mul_f32_e32 v55, 0xbfb8aa3b, v57
	v_exp_f32_e32 v54, v54
	v_exp_f32_e32 v55, v55
	v_cvt_pk_bf16_f32 v50, v50, v51
	v_pk_add_f32 v[54:55], v[54:55], 1.0 op_sel_hi:[1,0]
	s_nop 0
	v_div_scale_f32 v58, s[8:9], v55, v55, v57
	v_rcp_f32_e32 v59, v58
	s_nop 0
	v_fma_f32 v60, -v58, v59, 1.0
	v_fmac_f32_e32 v59, v60, v59
	v_div_scale_f32 v60, vcc, v57, v55, v57
	v_mul_f32_e32 v61, v60, v59
	v_fma_f32 v64, -v58, v61, v60
	v_fmac_f32_e32 v61, v64, v59
	v_fma_f32 v58, -v58, v61, v60
	v_div_fmas_f32 v58, v58, v59, v61
	v_div_fixup_f32 v55, v58, v55, v57
	v_div_scale_f32 v57, s[8:9], v54, v54, v56
	v_rcp_f32_e32 v58, v57
	s_nop 0
	v_fma_f32 v59, -v57, v58, 1.0
	v_fmac_f32_e32 v58, v59, v58
	v_div_scale_f32 v59, vcc, v56, v54, v56
	v_mul_f32_e32 v60, v59, v58
	v_fma_f32 v61, -v57, v60, v59
	v_fmac_f32_e32 v60, v61, v58
	v_fma_f32 v57, -v57, v60, v59
	v_div_fmas_f32 v57, v57, v58, v60
	v_div_fixup_f32 v54, v57, v54, v56
	v_pk_mul_f32 v[56:57], v[62:63], v[68:69] op_sel_hi:[1,0]
	s_nop 0
	v_pk_mul_f32 v[52:53], v[98:99], v[56:57]
	v_lshlrev_b32_e32 v56, 16, v190
	v_pk_mul_f32 v[52:53], v[54:55], v[52:53]
	v_and_b32_e32 v57, 0xffff0000, v190
	v_cvt_pk_bf16_f32 v51, v52, v53
	v_lshl_add_u64 v[52:53], v[202:203], 1, v[70:71]
	global_store_dwordx2 v[52:53], v[50:51], off
	v_mul_f32_e32 v54, 0xbfb8aa3b, v56
	v_mul_f32_e32 v55, 0xbfb8aa3b, v57
	v_exp_f32_e32 v54, v54
	v_exp_f32_e32 v55, v55
	s_waitcnt vmcnt(15)
	v_pk_mul_f32 v[32:33], v[100:101], v[32:33]
	v_pk_add_f32 v[54:55], v[54:55], 1.0 op_sel_hi:[1,0]
	v_pk_mul_f32 v[34:35], v[102:103], v[34:35]
	v_div_scale_f32 v58, s[8:9], v55, v55, v57
	v_rcp_f32_e32 v59, v58
	v_lshlrev_b32_e32 v52, 16, v188
	v_and_b32_e32 v53, 0xffff0000, v188
	v_fma_f32 v60, -v58, v59, 1.0
	v_fmac_f32_e32 v59, v60, v59
	v_div_scale_f32 v60, vcc, v57, v55, v57
	v_mul_f32_e32 v61, v60, v59
	v_fma_f32 v62, -v58, v61, v60
	v_fmac_f32_e32 v61, v62, v59
	v_fma_f32 v58, -v58, v61, v60
	v_div_fmas_f32 v58, v58, v59, v61
	v_div_fixup_f32 v55, v58, v55, v57
	v_div_scale_f32 v57, s[8:9], v54, v54, v56
	v_rcp_f32_e32 v58, v57
	s_nop 0
	v_fma_f32 v59, -v57, v58, 1.0
	v_fmac_f32_e32 v58, v59, v58
	v_div_scale_f32 v59, vcc, v56, v54, v56
	v_mul_f32_e32 v60, v59, v58
	v_fma_f32 v61, -v57, v60, v59
	v_fmac_f32_e32 v60, v61, v58
	v_fma_f32 v57, -v57, v60, v59
	v_div_fmas_f32 v57, v57, v58, v60
	v_div_fixup_f32 v54, v57, v54, v56
	v_pk_mul_f32 v[32:33], v[54:55], v[32:33]
	v_lshlrev_b32_e32 v54, 16, v191
	v_and_b32_e32 v55, 0xffff0000, v191
	v_mul_f32_e32 v50, 0xbfb8aa3b, v54
	v_mul_f32_e32 v51, 0xbfb8aa3b, v55
	v_exp_f32_e32 v50, v50
	v_exp_f32_e32 v51, v51
	v_cvt_pk_bf16_f32 v32, v32, v33
	v_pk_add_f32 v[50:51], v[50:51], 1.0 op_sel_hi:[1,0]
	s_nop 0
	v_div_scale_f32 v56, s[8:9], v51, v51, v55
	v_rcp_f32_e32 v57, v56
	s_nop 0
	v_fma_f32 v58, -v56, v57, 1.0
	v_fmac_f32_e32 v57, v58, v57
	v_div_scale_f32 v58, vcc, v55, v51, v55
	v_mul_f32_e32 v59, v58, v57
	v_fma_f32 v60, -v56, v59, v58
	v_fmac_f32_e32 v59, v60, v57
	v_fma_f32 v56, -v56, v59, v58
	v_div_fmas_f32 v56, v56, v57, v59
	v_div_fixup_f32 v51, v56, v51, v55
	v_div_scale_f32 v55, s[8:9], v50, v50, v54
	v_rcp_f32_e32 v56, v55
	s_nop 0
	v_fma_f32 v57, -v55, v56, 1.0
	v_fmac_f32_e32 v56, v57, v56
	v_div_scale_f32 v57, vcc, v54, v50, v54
	v_mul_f32_e32 v58, v57, v56
	v_fma_f32 v59, -v55, v58, v57
	v_fmac_f32_e32 v58, v59, v56
	v_fma_f32 v55, -v55, v58, v57
	v_div_fmas_f32 v55, v55, v56, v58
	v_div_fixup_f32 v50, v55, v50, v54
	v_pk_mul_f32 v[34:35], v[50:51], v[34:35]
	v_mul_f32_e32 v50, 0xbfb8aa3b, v52
	v_cvt_pk_bf16_f32 v33, v34, v35
	global_store_dwordx2 v[48:49], v[32:33], off offset:64
	v_mul_f32_e32 v51, 0xbfb8aa3b, v53
	v_exp_f32_e32 v50, v50
	v_exp_f32_e32 v51, v51
	s_waitcnt vmcnt(15)
; DI unsigned pk2(float lo, float hi) { f32x2 v = {lo, hi}; bf16x2_t b = __builtin_convertvector(v, bf16x2_t); return __builtin_bit_cast(unsigned, b); }
; DI float bflo(unsigned w) { return __uint_as_float(w << 16); }
; DI float bfhi(unsigned w) { return __uint_as_float(w & 0xffff0000u); }
; DI void gla_out_unit(int chunk, const Params& p, LAS unsigned char* lds) {
;     ...
;         for (int g = 0; g < 4; ++g) { const int v0 = 32 * vb + 8 * g + 4 * hi;
;             const u32x2 gw = gwv[vb][g];
;             const f32x4 gn = *(const f32x4*)(p.gla_og + h * 128 + v0);
;             float r[4] = {bflo(gw.x), bfhi(gw.x), bflo(gw.y), bfhi(gw.y)}; float ov[4];
; #pragma unroll
;             for (int e = 0; e < 4; ++e) { const float sg = r[e] / (1.0f + __expf(-r[e])); ov[e] = oT[vb][4 * g + e] * rstd * gn[e] * sg; }
;             u32x2 w; w.x = pk2(ov[0], ov[1]); w.y = pk2(ov[2], ov[3]);
;             *(u32x2*)(mix + (size_t)tok * DM + 512 + h * 128 + v0) = w; }
	v_pk_mul_f32 v[32:33], v[104:105], v[36:37]
	v_pk_add_f32 v[50:51], v[50:51], 1.0 op_sel_hi:[1,0]
	v_pk_mul_f32 v[34:35], v[106:107], v[38:39]
	v_div_scale_f32 v54, s[8:9], v51, v51, v53
	v_rcp_f32_e32 v55, v54
	v_lshlrev_b32_e32 v38, 16, v186
	v_and_b32_e32 v39, 0xffff0000, v186
	v_fma_f32 v56, -v54, v55, 1.0
	v_fmac_f32_e32 v55, v56, v55
	v_div_scale_f32 v56, vcc, v53, v51, v53
	v_mul_f32_e32 v57, v56, v55
	v_fma_f32 v58, -v54, v57, v56
	v_fmac_f32_e32 v57, v58, v55
	v_fma_f32 v54, -v54, v57, v56
	v_div_fmas_f32 v54, v54, v55, v57
	v_div_fixup_f32 v51, v54, v51, v53
	v_div_scale_f32 v53, s[8:9], v50, v50, v52
	v_rcp_f32_e32 v54, v53
	s_nop 0
	v_fma_f32 v55, -v53, v54, 1.0
	v_fmac_f32_e32 v54, v55, v54
	v_div_scale_f32 v55, vcc, v52, v50, v52
	v_mul_f32_e32 v56, v55, v54
	v_fma_f32 v57, -v53, v56, v55
	v_fmac_f32_e32 v56, v57, v54
	v_fma_f32 v53, -v53, v56, v55
	v_div_fmas_f32 v53, v53, v54, v56
	v_div_fixup_f32 v50, v53, v50, v52
	v_pk_mul_f32 v[32:33], v[50:51], v[32:33]
	v_lshlrev_b32_e32 v50, 16, v189
	v_and_b32_e32 v51, 0xffff0000, v189
	v_mul_f32_e32 v36, 0xbfb8aa3b, v50
	v_mul_f32_e32 v37, 0xbfb8aa3b, v51
	v_exp_f32_e32 v36, v36
	v_exp_f32_e32 v37, v37
	v_cvt_pk_bf16_f32 v32, v32, v33
	v_pk_add_f32 v[36:37], v[36:37], 1.0 op_sel_hi:[1,0]
	s_nop 0
	v_div_scale_f32 v52, s[8:9], v37, v37, v51
	v_rcp_f32_e32 v53, v52
	s_nop 0
	v_fma_f32 v54, -v52, v53, 1.0
	v_fmac_f32_e32 v53, v54, v53
	v_div_scale_f32 v54, vcc, v51, v37, v51
	v_mul_f32_e32 v55, v54, v53
	v_fma_f32 v56, -v52, v55, v54
	v_fmac_f32_e32 v55, v56, v53
	v_fma_f32 v52, -v52, v55, v54
	v_div_fmas_f32 v52, v52, v53, v55
	v_div_fixup_f32 v37, v52, v37, v51
	v_div_scale_f32 v51, s[8:9], v36, v36, v50
	v_rcp_f32_e32 v52, v51
	s_nop 0
	v_fma_f32 v53, -v51, v52, 1.0
	v_fmac_f32_e32 v52, v53, v52
	v_div_scale_f32 v53, vcc, v50, v36, v50
	v_mul_f32_e32 v54, v53, v52
	v_fma_f32 v55, -v51, v54, v53
	v_fmac_f32_e32 v54, v55, v52
	v_fma_f32 v51, -v51, v54, v53
	v_div_fmas_f32 v51, v51, v52, v54
	v_div_fixup_f32 v36, v51, v36, v50
	v_pk_mul_f32 v[34:35], v[36:37], v[34:35]
	v_mul_f32_e32 v36, 0xbfb8aa3b, v38
	v_cvt_pk_bf16_f32 v33, v34, v35
	global_store_dwordx2 v[48:49], v[32:33], off offset:80
	v_mul_f32_e32 v37, 0xbfb8aa3b, v39
	v_exp_f32_e32 v36, v36
	v_exp_f32_e32 v37, v37
	s_nop 0
	v_pk_add_f32 v[36:37], v[36:37], 1.0 op_sel_hi:[1,0]
	s_nop 0
	v_div_scale_f32 v50, s[8:9], v37, v37, v39
	v_rcp_f32_e32 v51, v50
	s_nop 0
	v_fma_f32 v52, -v50, v51, 1.0
	v_fmac_f32_e32 v51, v52, v51
	v_div_scale_f32 v52, vcc, v39, v37, v39
	v_mul_f32_e32 v53, v52, v51
	v_fma_f32 v54, -v50, v53, v52
	v_fmac_f32_e32 v53, v54, v51
	v_fma_f32 v50, -v50, v53, v52
	v_div_fmas_f32 v50, v50, v51, v53
	v_div_fixup_f32 v37, v50, v37, v39
	v_div_scale_f32 v39, s[8:9], v36, v36, v38
	v_rcp_f32_e32 v50, v39
	s_nop 0
	v_fma_f32 v51, -v39, v50, 1.0
	v_fmac_f32_e32 v50, v51, v50
	v_div_scale_f32 v51, vcc, v38, v36, v38
	v_mul_f32_e32 v52, v51, v50
	v_fma_f32 v53, -v39, v52, v51
	v_fmac_f32_e32 v52, v53, v50
	v_fma_f32 v39, -v39, v52, v51
	v_div_fmas_f32 v39, v39, v50, v52
	v_div_fixup_f32 v36, v39, v36, v38
	v_pk_mul_f32 v[38:39], v[40:41], v[68:69] op_sel_hi:[1,0]
	s_waitcnt vmcnt(15)
	v_pk_mul_f32 v[32:33], v[108:109], v[38:39]
	v_lshlrev_b32_e32 v38, 16, v187
	v_and_b32_e32 v39, 0xffff0000, v187
	v_pk_mul_f32 v[32:33], v[36:37], v[32:33]
	v_mul_f32_e32 v36, 0xbfb8aa3b, v38
	v_mul_f32_e32 v37, 0xbfb8aa3b, v39
	v_exp_f32_e32 v36, v36
	v_exp_f32_e32 v37, v37
	v_cvt_pk_bf16_f32 v32, v32, v33
	v_pk_add_f32 v[36:37], v[36:37], 1.0 op_sel_hi:[1,0]
	s_nop 0
	v_div_scale_f32 v40, s[8:9], v37, v37, v39
	v_rcp_f32_e32 v41, v40
	s_nop 0
	v_fma_f32 v50, -v40, v41, 1.0
	v_fmac_f32_e32 v41, v50, v41
	v_div_scale_f32 v50, vcc, v39, v37, v39
	v_mul_f32_e32 v51, v50, v41
	v_fma_f32 v52, -v40, v51, v50
	v_fmac_f32_e32 v51, v52, v41
	v_fma_f32 v40, -v40, v51, v50
	v_div_fmas_f32 v40, v40, v41, v51
	v_div_fixup_f32 v37, v40, v37, v39
	v_div_scale_f32 v39, s[8:9], v36, v36, v38
	v_rcp_f32_e32 v40, v39
	s_nop 0
	v_fma_f32 v41, -v39, v40, 1.0
	v_fmac_f32_e32 v40, v41, v40
	v_div_scale_f32 v41, vcc, v38, v36, v38
	v_mul_f32_e32 v50, v41, v40
	v_fma_f32 v51, -v39, v50, v41
	v_fmac_f32_e32 v50, v51, v40
	v_fma_f32 v39, -v39, v50, v41
	v_div_fmas_f32 v39, v39, v40, v50
	v_div_fixup_f32 v36, v39, v36, v38
	v_pk_mul_f32 v[38:39], v[42:43], v[68:69] op_sel_hi:[1,0]
	s_nop 0
	v_pk_mul_f32 v[34:35], v[110:111], v[38:39]
	v_lshlrev_b32_e32 v38, 16, v184
	v_pk_mul_f32 v[34:35], v[36:37], v[34:35]
	v_and_b32_e32 v39, 0xffff0000, v184
	v_cvt_pk_bf16_f32 v33, v34, v35
	global_store_dwordx2 v[48:49], v[32:33], off offset:96
	v_mul_f32_e32 v36, 0xbfb8aa3b, v38
	v_mul_f32_e32 v37, 0xbfb8aa3b, v39
	v_exp_f32_e32 v36, v36
	v_exp_f32_e32 v37, v37
	s_nop 0
	v_pk_add_f32 v[36:37], v[36:37], 1.0 op_sel_hi:[1,0]
	s_nop 0
	v_div_scale_f32 v40, s[8:9], v37, v37, v39
	v_rcp_f32_e32 v41, v40
	s_nop 0
	v_fma_f32 v42, -v40, v41, 1.0
	v_fmac_f32_e32 v41, v42, v41
	v_div_scale_f32 v42, vcc, v39, v37, v39
	v_mul_f32_e32 v43, v42, v41
	v_fma_f32 v50, -v40, v43, v42
	v_fmac_f32_e32 v43, v50, v41
	v_fma_f32 v40, -v40, v43, v42
	v_div_fmas_f32 v40, v40, v41, v43
	v_div_fixup_f32 v37, v40, v37, v39
	v_div_scale_f32 v39, s[8:9], v36, v36, v38
	v_rcp_f32_e32 v40, v39
	s_nop 0
	v_fma_f32 v41, -v39, v40, 1.0
	v_fmac_f32_e32 v40, v41, v40
	v_div_scale_f32 v41, vcc, v38, v36, v38
	v_mul_f32_e32 v42, v41, v40
	v_fma_f32 v43, -v39, v42, v41
	v_fmac_f32_e32 v42, v43, v40
	v_fma_f32 v39, -v39, v42, v41
	v_div_fmas_f32 v39, v39, v40, v42
	v_div_fixup_f32 v36, v39, v36, v38
	v_pk_mul_f32 v[38:39], v[44:45], v[68:69] op_sel_hi:[1,0]
	s_waitcnt vmcnt(15)
; DI unsigned pk2(float lo, float hi) { f32x2 v = {lo, hi}; bf16x2_t b = __builtin_convertvector(v, bf16x2_t); return __builtin_bit_cast(unsigned, b); }
; DI float bflo(unsigned w) { return __uint_as_float(w << 16); }
; DI float bfhi(unsigned w) { return __uint_as_float(w & 0xffff0000u); }
; DI void gla_out_unit(int chunk, const Params& p, LAS unsigned char* lds) {
;     ...
;         for (int g = 0; g < 4; ++g) { const int v0 = 32 * vb + 8 * g + 4 * hi;
;             const u32x2 gw = gwv[vb][g];
;             const f32x4 gn = *(const f32x4*)(p.gla_og + h * 128 + v0);
;             float r[4] = {bflo(gw.x), bfhi(gw.x), bflo(gw.y), bfhi(gw.y)}; float ov[4];
; #pragma unroll
;             for (int e = 0; e < 4; ++e) { const float sg = r[e] / (1.0f + __expf(-r[e])); ov[e] = oT[vb][4 * g + e] * rstd * gn[e] * sg; }
;             u32x2 w; w.x = pk2(ov[0], ov[1]); w.y = pk2(ov[2], ov[3]);
;             *(u32x2*)(mix + (size_t)tok * DM + 512 + h * 128 + v0) = w; }
	v_pk_mul_f32 v[32:33], v[112:113], v[38:39]
	v_lshlrev_b32_e32 v38, 16, v185
	v_and_b32_e32 v39, 0xffff0000, v185
	v_pk_mul_f32 v[32:33], v[36:37], v[32:33]
	v_mul_f32_e32 v36, 0xbfb8aa3b, v38
	v_mul_f32_e32 v37, 0xbfb8aa3b, v39
	v_exp_f32_e32 v36, v36
	v_exp_f32_e32 v37, v37
	v_cvt_pk_bf16_f32 v32, v32, v33
	v_pk_add_f32 v[36:37], v[36:37], 1.0 op_sel_hi:[1,0]
	s_nop 0
	v_div_scale_f32 v40, s[8:9], v37, v37, v39
	v_rcp_f32_e32 v41, v40
	s_nop 0
	v_fma_f32 v42, -v40, v41, 1.0
	v_fmac_f32_e32 v41, v42, v41
	v_div_scale_f32 v42, vcc, v39, v37, v39
	v_mul_f32_e32 v43, v42, v41
	v_fma_f32 v44, -v40, v43, v42
	v_fmac_f32_e32 v43, v44, v41
	v_fma_f32 v40, -v40, v43, v42
	v_div_fmas_f32 v40, v40, v41, v43
	v_div_fixup_f32 v37, v40, v37, v39
	v_div_scale_f32 v39, s[8:9], v36, v36, v38
	v_rcp_f32_e32 v40, v39
	s_nop 0
	v_fma_f32 v41, -v39, v40, 1.0
	v_fmac_f32_e32 v40, v41, v40
	v_div_scale_f32 v41, vcc, v38, v36, v38
	v_mul_f32_e32 v42, v41, v40
	v_fma_f32 v43, -v39, v42, v41
	v_fmac_f32_e32 v42, v43, v40
	v_fma_f32 v39, -v39, v42, v41
	v_div_fmas_f32 v39, v39, v40, v42
	v_div_fixup_f32 v36, v39, v36, v38
	v_pk_mul_f32 v[38:39], v[46:47], v[68:69] op_sel_hi:[1,0]
	s_nop 0
	v_pk_mul_f32 v[34:35], v[114:115], v[38:39]
	v_lshlrev_b32_e32 v38, 16, v182
	v_pk_mul_f32 v[34:35], v[36:37], v[34:35]
	v_and_b32_e32 v39, 0xffff0000, v182
	v_cvt_pk_bf16_f32 v33, v34, v35
	global_store_dwordx2 v[48:49], v[32:33], off offset:112
	v_mul_f32_e32 v36, 0xbfb8aa3b, v38
	v_mul_f32_e32 v37, 0xbfb8aa3b, v39
	v_exp_f32_e32 v36, v36
	v_exp_f32_e32 v37, v37
	s_waitcnt vmcnt(15)
	v_pk_mul_f32 v[16:17], v[116:117], v[16:17]
	v_pk_add_f32 v[36:37], v[36:37], 1.0 op_sel_hi:[1,0]
	v_pk_mul_f32 v[18:19], v[118:119], v[18:19]
	v_div_scale_f32 v40, s[8:9], v37, v37, v39
	v_rcp_f32_e32 v41, v40
	v_lshlrev_b32_e32 v34, 16, v180
	v_and_b32_e32 v35, 0xffff0000, v180
	v_fma_f32 v42, -v40, v41, 1.0
	v_fmac_f32_e32 v41, v42, v41
	v_div_scale_f32 v42, vcc, v39, v37, v39
	v_mul_f32_e32 v43, v42, v41
	v_fma_f32 v44, -v40, v43, v42
	v_fmac_f32_e32 v43, v44, v41
	v_fma_f32 v40, -v40, v43, v42
	v_div_fmas_f32 v40, v40, v41, v43
	v_div_fixup_f32 v37, v40, v37, v39
	v_div_scale_f32 v39, s[8:9], v36, v36, v38
	v_rcp_f32_e32 v40, v39
	s_nop 0
	v_fma_f32 v41, -v39, v40, 1.0
	v_fmac_f32_e32 v40, v41, v40
	v_div_scale_f32 v41, vcc, v38, v36, v38
	v_mul_f32_e32 v42, v41, v40
	v_fma_f32 v43, -v39, v42, v41
	v_fmac_f32_e32 v42, v43, v40
	v_fma_f32 v39, -v39, v42, v41
	v_div_fmas_f32 v39, v39, v40, v42
	v_div_fixup_f32 v36, v39, v36, v38
	v_pk_mul_f32 v[16:17], v[36:37], v[16:17]
	v_lshlrev_b32_e32 v36, 16, v183
	v_and_b32_e32 v37, 0xffff0000, v183
	v_mul_f32_e32 v32, 0xbfb8aa3b, v36
	v_mul_f32_e32 v33, 0xbfb8aa3b, v37
	v_exp_f32_e32 v32, v32
	v_exp_f32_e32 v33, v33
	v_cvt_pk_bf16_f32 v16, v16, v17
	v_pk_add_f32 v[32:33], v[32:33], 1.0 op_sel_hi:[1,0]
	s_nop 0
	v_div_scale_f32 v38, s[8:9], v33, v33, v37
	v_rcp_f32_e32 v39, v38
	s_nop 0
	v_fma_f32 v40, -v38, v39, 1.0
	v_fmac_f32_e32 v39, v40, v39
	v_div_scale_f32 v40, vcc, v37, v33, v37
	v_mul_f32_e32 v41, v40, v39
	v_fma_f32 v42, -v38, v41, v40
	v_fmac_f32_e32 v41, v42, v39
	v_fma_f32 v38, -v38, v41, v40
	v_div_fmas_f32 v38, v38, v39, v41
	v_div_fixup_f32 v33, v38, v33, v37
	v_div_scale_f32 v37, s[8:9], v32, v32, v36
	v_rcp_f32_e32 v38, v37
	s_nop 0
	v_fma_f32 v39, -v37, v38, 1.0
	v_fmac_f32_e32 v38, v39, v38
	v_div_scale_f32 v39, vcc, v36, v32, v36
	v_mul_f32_e32 v40, v39, v38
	v_fma_f32 v41, -v37, v40, v39
	v_fmac_f32_e32 v40, v41, v38
	v_fma_f32 v37, -v37, v40, v39
	v_div_fmas_f32 v37, v37, v38, v40
	v_div_fixup_f32 v32, v37, v32, v36
	v_pk_mul_f32 v[18:19], v[32:33], v[18:19]
	v_mul_f32_e32 v32, 0xbfb8aa3b, v34
	v_cvt_pk_bf16_f32 v17, v18, v19
	global_store_dwordx2 v[48:49], v[16:17], off offset:128
	v_mul_f32_e32 v33, 0xbfb8aa3b, v35
	v_exp_f32_e32 v32, v32
	v_exp_f32_e32 v33, v33
	s_waitcnt vmcnt(15)
	v_pk_mul_f32 v[16:17], v[120:121], v[20:21]
	v_pk_add_f32 v[32:33], v[32:33], 1.0 op_sel_hi:[1,0]
	v_pk_mul_f32 v[18:19], v[122:123], v[22:23]
	v_div_scale_f32 v36, s[8:9], v33, v33, v35
	v_rcp_f32_e32 v37, v36
	v_lshlrev_b32_e32 v22, 16, v178
	v_and_b32_e32 v23, 0xffff0000, v178
	v_fma_f32 v38, -v36, v37, 1.0
	v_fmac_f32_e32 v37, v38, v37
	v_div_scale_f32 v38, vcc, v35, v33, v35
	v_mul_f32_e32 v39, v38, v37
	v_fma_f32 v40, -v36, v39, v38
	v_fmac_f32_e32 v39, v40, v37
	v_fma_f32 v36, -v36, v39, v38
	v_div_fmas_f32 v36, v36, v37, v39
	v_div_fixup_f32 v33, v36, v33, v35
	v_div_scale_f32 v35, s[8:9], v32, v32, v34
	v_rcp_f32_e32 v36, v35
	s_nop 0
	v_fma_f32 v37, -v35, v36, 1.0
	v_fmac_f32_e32 v36, v37, v36
	v_div_scale_f32 v37, vcc, v34, v32, v34
	v_mul_f32_e32 v38, v37, v36
	v_fma_f32 v39, -v35, v38, v37
	v_fmac_f32_e32 v38, v39, v36
	v_fma_f32 v35, -v35, v38, v37
	v_div_fmas_f32 v35, v35, v36, v38
	v_div_fixup_f32 v32, v35, v32, v34
	v_pk_mul_f32 v[16:17], v[32:33], v[16:17]
	v_lshlrev_b32_e32 v32, 16, v181
	v_and_b32_e32 v33, 0xffff0000, v181
	v_mul_f32_e32 v20, 0xbfb8aa3b, v32
	v_mul_f32_e32 v21, 0xbfb8aa3b, v33
	v_exp_f32_e32 v20, v20
	v_exp_f32_e32 v21, v21
	v_cvt_pk_bf16_f32 v16, v16, v17
	v_pk_add_f32 v[20:21], v[20:21], 1.0 op_sel_hi:[1,0]
	s_nop 0
	v_div_scale_f32 v34, s[8:9], v21, v21, v33
	v_rcp_f32_e32 v35, v34
	s_nop 0
	v_fma_f32 v36, -v34, v35, 1.0
	v_fmac_f32_e32 v35, v36, v35
	v_div_scale_f32 v36, vcc, v33, v21, v33
	v_mul_f32_e32 v37, v36, v35
	v_fma_f32 v38, -v34, v37, v36
	v_fmac_f32_e32 v37, v38, v35
	v_fma_f32 v34, -v34, v37, v36
	v_div_fmas_f32 v34, v34, v35, v37
	v_div_fixup_f32 v21, v34, v21, v33
	v_div_scale_f32 v33, s[8:9], v20, v20, v32
	v_rcp_f32_e32 v34, v33
	s_nop 0
	v_fma_f32 v35, -v33, v34, 1.0
	v_fmac_f32_e32 v34, v35, v34
	v_div_scale_f32 v35, vcc, v32, v20, v32
	v_mul_f32_e32 v36, v35, v34
	v_fma_f32 v37, -v33, v36, v35
	v_fmac_f32_e32 v36, v37, v34
	v_fma_f32 v33, -v33, v36, v35
	v_div_fmas_f32 v33, v33, v34, v36
	v_div_fixup_f32 v20, v33, v20, v32
	v_pk_mul_f32 v[18:19], v[20:21], v[18:19]
	v_mul_f32_e32 v20, 0xbfb8aa3b, v22
	v_cvt_pk_bf16_f32 v17, v18, v19
	global_store_dwordx2 v[48:49], v[16:17], off offset:144
	v_mul_f32_e32 v21, 0xbfb8aa3b, v23
	v_exp_f32_e32 v20, v20
	v_exp_f32_e32 v21, v21
	s_nop 0
	v_pk_add_f32 v[20:21], v[20:21], 1.0 op_sel_hi:[1,0]
	s_nop 0
	v_div_scale_f32 v32, s[8:9], v21, v21, v23
	v_rcp_f32_e32 v33, v32
	s_nop 0
	v_fma_f32 v34, -v32, v33, 1.0
	v_fmac_f32_e32 v33, v34, v33
	v_div_scale_f32 v34, vcc, v23, v21, v23
	v_mul_f32_e32 v35, v34, v33
	v_fma_f32 v36, -v32, v35, v34
	v_fmac_f32_e32 v35, v36, v33
	v_fma_f32 v32, -v32, v35, v34
	v_div_fmas_f32 v32, v32, v33, v35
	v_div_fixup_f32 v21, v32, v21, v23
	v_div_scale_f32 v23, s[8:9], v20, v20, v22
	v_rcp_f32_e32 v32, v23
	s_nop 0
	v_fma_f32 v33, -v23, v32, 1.0
	v_fmac_f32_e32 v32, v33, v32
	v_div_scale_f32 v33, vcc, v22, v20, v22
	v_mul_f32_e32 v34, v33, v32
	v_fma_f32 v35, -v23, v34, v33
	v_fmac_f32_e32 v34, v35, v32
	v_fma_f32 v23, -v23, v34, v33
	v_div_fmas_f32 v23, v23, v32, v34
	v_div_fixup_f32 v20, v23, v20, v22
	v_pk_mul_f32 v[22:23], v[24:25], v[68:69] op_sel_hi:[1,0]
	s_waitcnt vmcnt(15)
; DI unsigned pk2(float lo, float hi) { f32x2 v = {lo, hi}; bf16x2_t b = __builtin_convertvector(v, bf16x2_t); return __builtin_bit_cast(unsigned, b); }
; DI float bflo(unsigned w) { return __uint_as_float(w << 16); }
; DI float bfhi(unsigned w) { return __uint_as_float(w & 0xffff0000u); }
; DI void gla_out_unit(int chunk, const Params& p, LAS unsigned char* lds) {
;     ...
;         for (int g = 0; g < 4; ++g) { const int v0 = 32 * vb + 8 * g + 4 * hi;
;             const u32x2 gw = gwv[vb][g];
;             const f32x4 gn = *(const f32x4*)(p.gla_og + h * 128 + v0);
;             float r[4] = {bflo(gw.x), bfhi(gw.x), bflo(gw.y), bfhi(gw.y)}; float ov[4];
; #pragma unroll
;             for (int e = 0; e < 4; ++e) { const float sg = r[e] / (1.0f + __expf(-r[e])); ov[e] = oT[vb][4 * g + e] * rstd * gn[e] * sg; }
;             u32x2 w; w.x = pk2(ov[0], ov[1]); w.y = pk2(ov[2], ov[3]);
;             *(u32x2*)(mix + (size_t)tok * DM + 512 + h * 128 + v0) = w; }
	v_pk_mul_f32 v[16:17], v[124:125], v[22:23]
	v_lshlrev_b32_e32 v22, 16, v179
	v_and_b32_e32 v23, 0xffff0000, v179
	v_pk_mul_f32 v[16:17], v[20:21], v[16:17]
	v_mul_f32_e32 v20, 0xbfb8aa3b, v22
	v_mul_f32_e32 v21, 0xbfb8aa3b, v23
	v_exp_f32_e32 v20, v20
	v_exp_f32_e32 v21, v21
	v_cvt_pk_bf16_f32 v16, v16, v17
	v_pk_add_f32 v[20:21], v[20:21], 1.0 op_sel_hi:[1,0]
	s_nop 0
	v_div_scale_f32 v24, s[8:9], v21, v21, v23
	v_rcp_f32_e32 v25, v24
	s_nop 0
	v_fma_f32 v32, -v24, v25, 1.0
	v_fmac_f32_e32 v25, v32, v25
	v_div_scale_f32 v32, vcc, v23, v21, v23
	v_mul_f32_e32 v33, v32, v25
	v_fma_f32 v34, -v24, v33, v32
	v_fmac_f32_e32 v33, v34, v25
	v_fma_f32 v24, -v24, v33, v32
	v_div_fmas_f32 v24, v24, v25, v33
	v_div_fixup_f32 v21, v24, v21, v23
	v_div_scale_f32 v23, s[8:9], v20, v20, v22
	v_rcp_f32_e32 v24, v23
	s_nop 0
	v_fma_f32 v25, -v23, v24, 1.0
	v_fmac_f32_e32 v24, v25, v24
	v_div_scale_f32 v25, vcc, v22, v20, v22
	v_mul_f32_e32 v32, v25, v24
	v_fma_f32 v33, -v23, v32, v25
	v_fmac_f32_e32 v32, v33, v24
	v_fma_f32 v23, -v23, v32, v25
	v_div_fmas_f32 v23, v23, v24, v32
	v_div_fixup_f32 v20, v23, v20, v22
	v_pk_mul_f32 v[22:23], v[26:27], v[68:69] op_sel_hi:[1,0]
	s_nop 0
	v_pk_mul_f32 v[18:19], v[126:127], v[22:23]
	v_lshlrev_b32_e32 v22, 16, v176
	v_pk_mul_f32 v[18:19], v[20:21], v[18:19]
	v_and_b32_e32 v23, 0xffff0000, v176
	v_cvt_pk_bf16_f32 v17, v18, v19
	global_store_dwordx2 v[48:49], v[16:17], off offset:160
	v_mul_f32_e32 v20, 0xbfb8aa3b, v22
	v_mul_f32_e32 v21, 0xbfb8aa3b, v23
	v_exp_f32_e32 v20, v20
	v_exp_f32_e32 v21, v21
	s_nop 0
	v_pk_add_f32 v[20:21], v[20:21], 1.0 op_sel_hi:[1,0]
	s_nop 0
	v_div_scale_f32 v24, s[8:9], v21, v21, v23
	v_rcp_f32_e32 v25, v24
	s_nop 0
	v_fma_f32 v26, -v24, v25, 1.0
	v_fmac_f32_e32 v25, v26, v25
	v_div_scale_f32 v26, vcc, v23, v21, v23
	v_mul_f32_e32 v27, v26, v25
	v_fma_f32 v32, -v24, v27, v26
	v_fmac_f32_e32 v27, v32, v25
	v_fma_f32 v24, -v24, v27, v26
	v_div_fmas_f32 v24, v24, v25, v27
	v_div_fixup_f32 v21, v24, v21, v23
	v_div_scale_f32 v23, s[8:9], v20, v20, v22
	v_rcp_f32_e32 v24, v23
	s_nop 0
	v_fma_f32 v25, -v23, v24, 1.0
	v_fmac_f32_e32 v24, v25, v24
	v_div_scale_f32 v25, vcc, v22, v20, v22
	v_mul_f32_e32 v26, v25, v24
	v_fma_f32 v27, -v23, v26, v25
	v_fmac_f32_e32 v26, v27, v24
	v_fma_f32 v23, -v23, v26, v25
	v_div_fmas_f32 v23, v23, v24, v26
	v_div_fixup_f32 v20, v23, v20, v22
	v_pk_mul_f32 v[22:23], v[28:29], v[68:69] op_sel_hi:[1,0]
	s_waitcnt vmcnt(15)
	v_pk_mul_f32 v[16:17], v[128:129], v[22:23]
	v_lshlrev_b32_e32 v22, 16, v177
	v_and_b32_e32 v23, 0xffff0000, v177
	v_pk_mul_f32 v[16:17], v[20:21], v[16:17]
	v_mul_f32_e32 v20, 0xbfb8aa3b, v22
	v_mul_f32_e32 v21, 0xbfb8aa3b, v23
	v_exp_f32_e32 v20, v20
	v_exp_f32_e32 v21, v21
	v_cvt_pk_bf16_f32 v16, v16, v17
	v_pk_add_f32 v[20:21], v[20:21], 1.0 op_sel_hi:[1,0]
	s_nop 0
	v_div_scale_f32 v24, s[8:9], v21, v21, v23
	v_rcp_f32_e32 v25, v24
	s_nop 0
	v_fma_f32 v26, -v24, v25, 1.0
	v_fmac_f32_e32 v25, v26, v25
	v_div_scale_f32 v26, vcc, v23, v21, v23
	v_mul_f32_e32 v27, v26, v25
	v_fma_f32 v28, -v24, v27, v26
	v_fmac_f32_e32 v27, v28, v25
	v_fma_f32 v24, -v24, v27, v26
	v_div_fmas_f32 v24, v24, v25, v27
	v_div_fixup_f32 v21, v24, v21, v23
	v_div_scale_f32 v23, s[8:9], v20, v20, v22
	v_rcp_f32_e32 v24, v23
	s_nop 0
	v_fma_f32 v25, -v23, v24, 1.0
	v_fmac_f32_e32 v24, v25, v24
	v_div_scale_f32 v25, vcc, v22, v20, v22
	v_mul_f32_e32 v26, v25, v24
	v_fma_f32 v27, -v23, v26, v25
	v_fmac_f32_e32 v26, v27, v24
	v_fma_f32 v23, -v23, v26, v25
	v_div_fmas_f32 v23, v23, v24, v26
	v_div_fixup_f32 v20, v23, v20, v22
	v_pk_mul_f32 v[22:23], v[30:31], v[68:69] op_sel_hi:[1,0]
	s_nop 0
	v_pk_mul_f32 v[18:19], v[130:131], v[22:23]
	v_lshlrev_b32_e32 v22, 16, v174
	v_pk_mul_f32 v[18:19], v[20:21], v[18:19]
	v_and_b32_e32 v23, 0xffff0000, v174
	v_cvt_pk_bf16_f32 v17, v18, v19
	global_store_dwordx2 v[48:49], v[16:17], off offset:176
	v_mul_f32_e32 v20, 0xbfb8aa3b, v22
	v_mul_f32_e32 v21, 0xbfb8aa3b, v23
	v_exp_f32_e32 v20, v20
	v_exp_f32_e32 v21, v21
	s_waitcnt vmcnt(15)
	v_pk_mul_f32 v[0:1], v[132:133], v[0:1]
	v_pk_add_f32 v[20:21], v[20:21], 1.0 op_sel_hi:[1,0]
	v_pk_mul_f32 v[2:3], v[134:135], v[2:3]
	v_div_scale_f32 v24, s[8:9], v21, v21, v23
	v_rcp_f32_e32 v25, v24
	v_lshlrev_b32_e32 v18, 16, v172
	v_and_b32_e32 v19, 0xffff0000, v172
	v_fma_f32 v26, -v24, v25, 1.0
	v_fmac_f32_e32 v25, v26, v25
	v_div_scale_f32 v26, vcc, v23, v21, v23
	v_mul_f32_e32 v27, v26, v25
	v_fma_f32 v28, -v24, v27, v26
	v_fmac_f32_e32 v27, v28, v25
	v_fma_f32 v24, -v24, v27, v26
	v_div_fmas_f32 v24, v24, v25, v27
	v_div_fixup_f32 v21, v24, v21, v23
	v_div_scale_f32 v23, s[8:9], v20, v20, v22
	v_rcp_f32_e32 v24, v23
	s_nop 0
	v_fma_f32 v25, -v23, v24, 1.0
	v_fmac_f32_e32 v24, v25, v24
	v_div_scale_f32 v25, vcc, v22, v20, v22
	v_mul_f32_e32 v26, v25, v24
	v_fma_f32 v27, -v23, v26, v25
	v_fmac_f32_e32 v26, v27, v24
	v_fma_f32 v23, -v23, v26, v25
	v_div_fmas_f32 v23, v23, v24, v26
	v_div_fixup_f32 v20, v23, v20, v22
	v_pk_mul_f32 v[0:1], v[20:21], v[0:1]
	v_lshlrev_b32_e32 v20, 16, v175
	v_and_b32_e32 v21, 0xffff0000, v175
	v_mul_f32_e32 v16, 0xbfb8aa3b, v20
	v_mul_f32_e32 v17, 0xbfb8aa3b, v21
	v_exp_f32_e32 v16, v16
	v_exp_f32_e32 v17, v17
	v_cvt_pk_bf16_f32 v0, v0, v1
	v_pk_add_f32 v[16:17], v[16:17], 1.0 op_sel_hi:[1,0]
	s_nop 0
	v_div_scale_f32 v22, s[8:9], v17, v17, v21
	v_rcp_f32_e32 v23, v22
	s_nop 0
	v_fma_f32 v24, -v22, v23, 1.0
	v_fmac_f32_e32 v23, v24, v23
	v_div_scale_f32 v24, vcc, v21, v17, v21
	v_mul_f32_e32 v25, v24, v23
	v_fma_f32 v26, -v22, v25, v24
	v_fmac_f32_e32 v25, v26, v23
	v_fma_f32 v22, -v22, v25, v24
	v_div_fmas_f32 v22, v22, v23, v25
	v_div_fixup_f32 v17, v22, v17, v21
	v_div_scale_f32 v21, s[8:9], v16, v16, v20
	v_rcp_f32_e32 v22, v21
	s_nop 0
	v_fma_f32 v23, -v21, v22, 1.0
	v_fmac_f32_e32 v22, v23, v22
	v_div_scale_f32 v23, vcc, v20, v16, v20
	v_mul_f32_e32 v24, v23, v22
	v_fma_f32 v25, -v21, v24, v23
	v_fmac_f32_e32 v24, v25, v22
	v_fma_f32 v21, -v21, v24, v23
	v_div_fmas_f32 v21, v21, v22, v24
	v_div_fixup_f32 v16, v21, v16, v20
	v_pk_mul_f32 v[2:3], v[16:17], v[2:3]
	v_mul_f32_e32 v16, 0xbfb8aa3b, v18
	v_cvt_pk_bf16_f32 v1, v2, v3
	global_store_dwordx2 v[48:49], v[0:1], off offset:192
	v_mul_f32_e32 v17, 0xbfb8aa3b, v19
	v_exp_f32_e32 v16, v16
	v_exp_f32_e32 v17, v17
	s_waitcnt vmcnt(15)
; DI unsigned pk2(float lo, float hi) { f32x2 v = {lo, hi}; bf16x2_t b = __builtin_convertvector(v, bf16x2_t); return __builtin_bit_cast(unsigned, b); }
; DI float bflo(unsigned w) { return __uint_as_float(w << 16); }
; DI float bfhi(unsigned w) { return __uint_as_float(w & 0xffff0000u); }
; DI void gla_out_unit(int chunk, const Params& p, LAS unsigned char* lds) {
;     ...
;         for (int g = 0; g < 4; ++g) { const int v0 = 32 * vb + 8 * g + 4 * hi;
;             const u32x2 gw = gwv[vb][g];
;             const f32x4 gn = *(const f32x4*)(p.gla_og + h * 128 + v0);
;             float r[4] = {bflo(gw.x), bfhi(gw.x), bflo(gw.y), bfhi(gw.y)}; float ov[4];
; #pragma unroll
;             for (int e = 0; e < 4; ++e) { const float sg = r[e] / (1.0f + __expf(-r[e])); ov[e] = oT[vb][4 * g + e] * rstd * gn[e] * sg; }
;             u32x2 w; w.x = pk2(ov[0], ov[1]); w.y = pk2(ov[2], ov[3]);
;             *(u32x2*)(mix + (size_t)tok * DM + 512 + h * 128 + v0) = w; }
	v_pk_mul_f32 v[0:1], v[136:137], v[4:5]
	v_pk_add_f32 v[16:17], v[16:17], 1.0 op_sel_hi:[1,0]
	v_pk_mul_f32 v[2:3], v[138:139], v[6:7]
	v_div_scale_f32 v20, s[8:9], v17, v17, v19
	v_rcp_f32_e32 v21, v20
	v_lshlrev_b32_e32 v6, 16, v170
	v_and_b32_e32 v7, 0xffff0000, v170
	v_fma_f32 v22, -v20, v21, 1.0
	v_fmac_f32_e32 v21, v22, v21
	v_div_scale_f32 v22, vcc, v19, v17, v19
	v_mul_f32_e32 v23, v22, v21
	v_fma_f32 v24, -v20, v23, v22
	v_fmac_f32_e32 v23, v24, v21
	v_fma_f32 v20, -v20, v23, v22
	v_div_fmas_f32 v20, v20, v21, v23
	v_div_fixup_f32 v17, v20, v17, v19
	v_div_scale_f32 v19, s[8:9], v16, v16, v18
	v_rcp_f32_e32 v20, v19
	s_nop 0
	v_fma_f32 v21, -v19, v20, 1.0
	v_fmac_f32_e32 v20, v21, v20
	v_div_scale_f32 v21, vcc, v18, v16, v18
	v_mul_f32_e32 v22, v21, v20
	v_fma_f32 v23, -v19, v22, v21
	v_fmac_f32_e32 v22, v23, v20
	v_fma_f32 v19, -v19, v22, v21
	v_div_fmas_f32 v19, v19, v20, v22
	v_div_fixup_f32 v16, v19, v16, v18
	v_pk_mul_f32 v[0:1], v[16:17], v[0:1]
	v_lshlrev_b32_e32 v16, 16, v173
	v_and_b32_e32 v17, 0xffff0000, v173
	v_mul_f32_e32 v4, 0xbfb8aa3b, v16
	v_mul_f32_e32 v5, 0xbfb8aa3b, v17
	v_exp_f32_e32 v4, v4
	v_exp_f32_e32 v5, v5
	v_cvt_pk_bf16_f32 v0, v0, v1
	v_pk_add_f32 v[4:5], v[4:5], 1.0 op_sel_hi:[1,0]
	s_nop 0
	v_div_scale_f32 v18, s[8:9], v5, v5, v17
	v_rcp_f32_e32 v19, v18
	s_nop 0
	v_fma_f32 v20, -v18, v19, 1.0
	v_fmac_f32_e32 v19, v20, v19
	v_div_scale_f32 v20, vcc, v17, v5, v17
	v_mul_f32_e32 v21, v20, v19
	v_fma_f32 v22, -v18, v21, v20
	v_fmac_f32_e32 v21, v22, v19
	v_fma_f32 v18, -v18, v21, v20
	v_div_fmas_f32 v18, v18, v19, v21
	v_div_fixup_f32 v5, v18, v5, v17
	v_div_scale_f32 v17, s[8:9], v4, v4, v16
	v_rcp_f32_e32 v18, v17
	s_nop 0
	v_fma_f32 v19, -v17, v18, 1.0
	v_fmac_f32_e32 v18, v19, v18
	v_div_scale_f32 v19, vcc, v16, v4, v16
	v_mul_f32_e32 v20, v19, v18
	v_fma_f32 v21, -v17, v20, v19
	v_fmac_f32_e32 v20, v21, v18
	v_fma_f32 v17, -v17, v20, v19
	v_div_fmas_f32 v17, v17, v18, v20
	v_div_fixup_f32 v4, v17, v4, v16
	v_pk_mul_f32 v[2:3], v[4:5], v[2:3]
	v_mul_f32_e32 v4, 0xbfb8aa3b, v6
	v_cvt_pk_bf16_f32 v1, v2, v3
	global_store_dwordx2 v[48:49], v[0:1], off offset:208
	v_mul_f32_e32 v5, 0xbfb8aa3b, v7
	v_exp_f32_e32 v4, v4
	v_exp_f32_e32 v5, v5
	s_nop 0
	v_pk_add_f32 v[4:5], v[4:5], 1.0 op_sel_hi:[1,0]
	s_nop 0
	v_div_scale_f32 v16, s[8:9], v5, v5, v7
	v_rcp_f32_e32 v17, v16
	s_nop 0
	v_fma_f32 v18, -v16, v17, 1.0
	v_fmac_f32_e32 v17, v18, v17
	v_div_scale_f32 v18, vcc, v7, v5, v7
	v_mul_f32_e32 v19, v18, v17
	v_fma_f32 v20, -v16, v19, v18
	v_fmac_f32_e32 v19, v20, v17
	v_fma_f32 v16, -v16, v19, v18
	v_div_fmas_f32 v16, v16, v17, v19
	v_div_fixup_f32 v5, v16, v5, v7
	v_div_scale_f32 v7, s[8:9], v4, v4, v6
	v_rcp_f32_e32 v16, v7
	s_nop 0
	v_fma_f32 v17, -v7, v16, 1.0
	v_fmac_f32_e32 v16, v17, v16
	v_div_scale_f32 v17, vcc, v6, v4, v6
	v_mul_f32_e32 v18, v17, v16
	v_fma_f32 v19, -v7, v18, v17
	v_fmac_f32_e32 v18, v19, v16
	v_fma_f32 v7, -v7, v18, v17
	v_div_fmas_f32 v7, v7, v16, v18
	v_div_fixup_f32 v4, v7, v4, v6
	v_pk_mul_f32 v[6:7], v[8:9], v[68:69] op_sel_hi:[1,0]
	s_waitcnt vmcnt(15)
	v_pk_mul_f32 v[0:1], v[140:141], v[6:7]
	v_lshlrev_b32_e32 v6, 16, v171
	v_and_b32_e32 v7, 0xffff0000, v171
	v_pk_mul_f32 v[0:1], v[4:5], v[0:1]
	v_mul_f32_e32 v4, 0xbfb8aa3b, v6
	v_mul_f32_e32 v5, 0xbfb8aa3b, v7
	v_exp_f32_e32 v4, v4
	v_exp_f32_e32 v5, v5
	v_cvt_pk_bf16_f32 v0, v0, v1
	v_pk_add_f32 v[4:5], v[4:5], 1.0 op_sel_hi:[1,0]
	s_nop 0
	v_div_scale_f32 v8, s[8:9], v5, v5, v7
	v_rcp_f32_e32 v9, v8
	s_nop 0
	v_fma_f32 v16, -v8, v9, 1.0
	v_fmac_f32_e32 v9, v16, v9
	v_div_scale_f32 v16, vcc, v7, v5, v7
	v_mul_f32_e32 v17, v16, v9
	v_fma_f32 v18, -v8, v17, v16
	v_fmac_f32_e32 v17, v18, v9
	v_fma_f32 v8, -v8, v17, v16
	v_div_fmas_f32 v8, v8, v9, v17
	v_div_fixup_f32 v5, v8, v5, v7
	v_div_scale_f32 v7, s[8:9], v4, v4, v6
	v_rcp_f32_e32 v8, v7
	s_nop 0
	v_fma_f32 v9, -v7, v8, 1.0
	v_fmac_f32_e32 v8, v9, v8
	v_div_scale_f32 v9, vcc, v6, v4, v6
	v_mul_f32_e32 v16, v9, v8
	v_fma_f32 v17, -v7, v16, v9
	v_fmac_f32_e32 v16, v17, v8
	v_fma_f32 v7, -v7, v16, v9
	v_div_fmas_f32 v7, v7, v8, v16
	v_div_fixup_f32 v4, v7, v4, v6
	v_pk_mul_f32 v[6:7], v[10:11], v[68:69] op_sel_hi:[1,0]
	s_nop 0
	v_pk_mul_f32 v[2:3], v[142:143], v[6:7]
	v_lshlrev_b32_e32 v6, 16, v168
	v_pk_mul_f32 v[2:3], v[4:5], v[2:3]
	v_and_b32_e32 v7, 0xffff0000, v168
	v_cvt_pk_bf16_f32 v1, v2, v3
	global_store_dwordx2 v[48:49], v[0:1], off offset:224
	v_mul_f32_e32 v4, 0xbfb8aa3b, v6
	v_mul_f32_e32 v5, 0xbfb8aa3b, v7
	v_exp_f32_e32 v4, v4
	v_exp_f32_e32 v5, v5
	s_nop 0
	v_pk_add_f32 v[4:5], v[4:5], 1.0 op_sel_hi:[1,0]
	s_nop 0
	v_div_scale_f32 v8, s[8:9], v5, v5, v7
	v_rcp_f32_e32 v9, v8
	s_nop 0
	v_fma_f32 v10, -v8, v9, 1.0
	v_fmac_f32_e32 v9, v10, v9
	v_div_scale_f32 v10, vcc, v7, v5, v7
	v_mul_f32_e32 v11, v10, v9
	v_fma_f32 v16, -v8, v11, v10
	v_fmac_f32_e32 v11, v16, v9
	v_fma_f32 v8, -v8, v11, v10
	v_div_fmas_f32 v8, v8, v9, v11
	v_div_fixup_f32 v5, v8, v5, v7
	v_div_scale_f32 v7, s[8:9], v4, v4, v6
	v_rcp_f32_e32 v8, v7
	s_nop 0
	v_fma_f32 v9, -v7, v8, 1.0
	v_fmac_f32_e32 v8, v9, v8
	v_div_scale_f32 v9, vcc, v6, v4, v6
	v_mul_f32_e32 v10, v9, v8
	v_fma_f32 v11, -v7, v10, v9
	v_fmac_f32_e32 v10, v11, v8
	v_fma_f32 v7, -v7, v10, v9
	v_div_fmas_f32 v7, v7, v8, v10
	v_div_fixup_f32 v4, v7, v4, v6
	v_pk_mul_f32 v[6:7], v[12:13], v[68:69] op_sel_hi:[1,0]
	s_waitcnt vmcnt(15)
	v_pk_mul_f32 v[0:1], v[144:145], v[6:7]
	v_lshlrev_b32_e32 v6, 16, v169
	v_and_b32_e32 v7, 0xffff0000, v169
	v_pk_mul_f32 v[0:1], v[4:5], v[0:1]
	v_mul_f32_e32 v4, 0xbfb8aa3b, v6
	v_mul_f32_e32 v5, 0xbfb8aa3b, v7
	v_exp_f32_e32 v4, v4
	v_exp_f32_e32 v5, v5
	v_cvt_pk_bf16_f32 v0, v0, v1
	v_pk_add_f32 v[4:5], v[4:5], 1.0 op_sel_hi:[1,0]
	s_nop 0
	v_div_scale_f32 v8, s[8:9], v5, v5, v7
	v_rcp_f32_e32 v9, v8
	s_nop 0
	v_fma_f32 v10, -v8, v9, 1.0
	v_fmac_f32_e32 v9, v10, v9
	v_div_scale_f32 v10, vcc, v7, v5, v7
	v_mul_f32_e32 v11, v10, v9
	v_fma_f32 v12, -v8, v11, v10
	v_fmac_f32_e32 v11, v12, v9
	v_fma_f32 v8, -v8, v11, v10
	v_div_fmas_f32 v8, v8, v9, v11
	v_div_fixup_f32 v5, v8, v5, v7
	v_div_scale_f32 v7, s[8:9], v4, v4, v6
	v_rcp_f32_e32 v8, v7
	s_nop 0
	v_fma_f32 v9, -v7, v8, 1.0
	v_fmac_f32_e32 v8, v9, v8
	v_div_scale_f32 v9, vcc, v6, v4, v6
	v_mul_f32_e32 v10, v9, v8
	v_fma_f32 v11, -v7, v10, v9
	v_fmac_f32_e32 v10, v11, v8
	v_fma_f32 v7, -v7, v10, v9
	v_div_fmas_f32 v7, v7, v8, v10
	v_div_fixup_f32 v4, v7, v4, v6
	v_pk_mul_f32 v[6:7], v[14:15], v[68:69] op_sel_hi:[1,0]
	s_nop 0
	v_pk_mul_f32 v[2:3], v[146:147], v[6:7]
	s_nop 0
	v_pk_mul_f32 v[2:3], v[4:5], v[2:3]
	s_nop 0
	v_cvt_pk_bf16_f32 v1, v2, v3
	global_store_dwordx2 v[48:49], v[0:1], off offset:240
	s_barrier
	s_cbranch_scc1 .LBB0_624
; #define LAS __attribute__((address_space(3)))
; DI int get_tid() { int t = threadIdx.x; asm volatile("" : "+v"(t)); return t; }
; DI void gla_out_unit(int chunk, const Params& p, LAS unsigned char* lds) {
;     const int tid = get_tid(), lane = tid & 63, wid = __builtin_amdgcn_readfirstlane(tid >> 6), r32 = lane & 31, hi = lane >> 5;
;     const bf16_t* proj = (const bf16_t*)(p.ws + WS_PROJ);
;     const int b = chunk >> 7, n = chunk & 127, tok0 = chunk * 64;
;     LAS bf16_t* vT = (LAS bf16_t*)(lds + L2_VT);
;     const int h = wid >> 1, cb = wid & 1, bh = b * 4 + h, tok = tok0 + 32 * cb + r32;
;     bf16x8 qf[4], kf[2][4], sf[4][4];
; #pragma unroll
;     for (int ks = 0; ks < 4; ++ks) qf[ks] = *(const bf16x8*)(proj + (size_t)tok * NPROJ + C_GQ + h * 64 + 16 * ks + 8 * hi);
; #pragma unroll
;     for (int sb = 0; sb < 2; ++sb)
; #pragma unroll
;         for (int ks = 0; ks < 4; ++ks) kf[sb][ks] = *(const bf16x8*)(proj + (size_t)(tok0 + 32 * sb + r32) * NPROJ + C_GK + h * 64 + 16 * ks + 8 * hi);
;     const bf16_t* sp = (const bf16_t*)(p.ws + WS_SPT) + ((size_t)bh * 128 + n) * 8192;
; #pragma unroll
;     for (int vb = 0; vb < 4; ++vb)
; #pragma unroll
;         for (int ks = 0; ks < 4; ++ks) sf[vb][ks] = *(const bf16x8*)(sp + (32 * vb + r32) * 64 + 16 * ks + 8 * hi);
;     u32x2 gwv[4][4];
; #pragma unroll
;     for (int vb = 0; vb < 4; ++vb)
; #pragma unroll
;         for (int g = 0; g < 4; ++g) gwv[vb][g] = *(const u32x2*)(proj + (size_t)tok * NPROJ + C_GR + h * 128 + 32 * vb + 8 * g + 4 * hi);
;     stage_vT(proj, tok0, lds, tid);
.LBB0_618:
	v_mov_b32_e32 v202, v208
	s_ashr_i32 s8, s12, 5
	v_readfirstlane_b32 s13, v202
	s_and_b32 s21, s8, -4
	s_lshr_b32 s8, s13, 1
	s_and_b32 s8, s8, 32
	v_and_b32_e32 v199, 31, v202
	s_add_i32 s8, s0, s8
	v_add_u32_e32 v198, s8, v199
	s_ashr_i32 s20, s13, 7
	v_mad_i64_i32 v[68:69], s[8:9], v198, s5, v[160:161]
	s_lshl_b32 s8, s20, 6
	s_ashr_i32 s9, s8, 31
	v_bfe_u32 v70, v202, 5, 1
	s_lshl_b64 s[8:9], s[8:9], 1
	v_lshl_add_u64 v[0:1], v[68:69], 0, s[8:9]
	v_lshlrev_b32_e32 v4, 4, v70
	v_mov_b32_e32 v5, v167
	v_lshl_add_u64 v[0:1], v[0:1], 0, v[4:5]
	v_add_u32_e32 v8, s0, v199
	global_load_dwordx4 v[140:143], v[0:1], off offset:3072
	global_load_dwordx4 v[136:139], v[0:1], off offset:3104
	global_load_dwordx4 v[132:135], v[0:1], off offset:3136
	global_load_dwordx4 v[128:131], v[0:1], off offset:3168
	v_mad_i64_i32 v[0:1], s[18:19], v8, s5, v[160:161]
	v_lshl_add_u64 v[0:1], v[0:1], 0, s[8:9]
	v_lshl_add_u64 v[6:7], v[0:1], 0, v[4:5]
	global_load_dwordx4 v[0:3], v[6:7], off offset:3584
	global_load_dwordx4 v[24:27], v[6:7], off offset:3616
	global_load_dwordx4 v[20:23], v[6:7], off offset:3648
	global_load_dwordx4 v[16:19], v[6:7], off offset:3680
	v_add_u32_e32 v6, 32, v8
	v_mad_i64_i32 v[6:7], s[18:19], v6, s5, v[160:161]
	v_lshl_add_u64 v[6:7], v[6:7], 0, s[8:9]
	s_add_i32 s8, s20, s21
	s_ashr_i32 s9, s8, 31
	s_and_b32 s18, s1, 0xfe000
	s_lshl_b64 s[8:9], s[8:9], 21
	s_add_u32 s8, s94, s8
	s_addc_u32 s9, s95, s9
	s_lshl_b32 s18, s18, 1
	s_add_u32 s8, s8, s18
	v_lshl_add_u64 v[6:7], v[6:7], 0, v[4:5]
	s_addc_u32 s9, s9, 0
	global_load_dwordx4 v[156:159], v[6:7], off offset:3584
	global_load_dwordx4 v[152:155], v[6:7], off offset:3616
	global_load_dwordx4 v[148:151], v[6:7], off offset:3648
	global_load_dwordx4 v[144:147], v[6:7], off offset:3680
	v_lshl_add_u64 v[4:5], s[8:9], 0, v[4:5]
	v_lshlrev_b32_e32 v6, 7, v199
	v_mov_b32_e32 v7, v167
	v_lshl_add_u64 v[4:5], v[4:5], 0, v[6:7]
	v_add_co_u32_e32 v6, vcc, s6, v4
	s_movk_i32 s8, 0x2000
	s_nop 0
	v_addc_co_u32_e32 v7, vcc, 0, v5, vcc
	v_add_co_u32_e32 v8, vcc, s8, v4
	s_and_b32 s22, s13, 0xffffff80
	s_nop 0
	v_addc_co_u32_e32 v9, vcc, 0, v5, vcc
	s_movk_i32 s8, 0x3000
	s_ashr_i32 s23, s22, 31
	v_lshlrev_b32_e32 v166, 3, v70
	global_load_dwordx4 v[64:67], v[4:5], off
	global_load_dwordx4 v[88:91], v[4:5], off offset:32
	global_load_dwordx4 v[84:87], v[4:5], off offset:64
	global_load_dwordx4 v[80:83], v[4:5], off offset:96
	v_add_co_u32_e32 v4, vcc, s8, v4
	v_lshl_add_u64 v[68:69], s[22:23], 1, v[68:69]
	s_nop 0
	v_addc_co_u32_e32 v5, vcc, 0, v5, vcc
	v_lshl_add_u64 v[68:69], v[68:69], 0, v[166:167]
	s_mov_b64 s[8:9], 0x1400
	v_lshlrev_b32_e32 v203, 2, v70
	v_lshl_add_u64 v[70:71], v[68:69], 0, s[8:9]
	v_add_co_u32_e32 v68, vcc, s6, v68
	s_waitcnt vmcnt(48)
	v_ashrrev_i32_e32 v113, 6, v202
	v_addc_co_u32_e32 v69, vcc, 0, v69, vcc
	global_load_dwordx4 v[60:63], v[8:9], off offset:-4096
	global_load_dwordx4 v[56:59], v[6:7], off offset:32
	global_load_dwordx4 v[52:55], v[6:7], off offset:64
	global_load_dwordx4 v[48:51], v[6:7], off offset:96
	global_load_dwordx4 v[44:47], v[8:9], off
	global_load_dwordx4 v[40:43], v[8:9], off offset:32
	global_load_dwordx4 v[36:39], v[8:9], off offset:64
	global_load_dwordx4 v[32:35], v[8:9], off offset:96
	global_load_dwordx4 v[28:31], v[4:5], off
	global_load_dwordx4 v[12:15], v[4:5], off offset:32
	s_nop 0
	global_load_dwordx4 v[8:11], v[4:5], off offset:64
	s_nop 0
	global_load_dwordx4 v[4:7], v[4:5], off offset:96
	s_nop 0
	v_mov_b64_e32 v[224:225], v[68:69]
	v_mov_b64_e32 v[226:227], v[70:71]
	v_add_u32_e32 v68, s0, v113
	v_lshlrev_b32_e32 v70, 4, v202
	v_add_u32_e32 v72, 0x200, v202
	v_mad_i64_i32 v[68:69], s[8:9], v68, s5, v[160:161]
	v_and_b32_e32 v166, 0x3f0, v70
	v_ashrrev_i32_e32 v116, 6, v72
	v_lshl_add_u64 v[68:69], v[68:69], 0, v[166:167]
	v_add_u32_e32 v72, s0, v116
	v_add_u32_e32 v76, 0x400, v202
	v_add_co_u32_e32 v68, vcc, s6, v68
	v_mad_i64_i32 v[72:73], s[8:9], v72, s5, v[160:161]
	v_ashrrev_i32_e32 v117, 6, v76
	v_addc_co_u32_e32 v69, vcc, 0, v69, vcc
	v_lshl_add_u64 v[72:73], v[72:73], 0, v[166:167]
	v_add_u32_e32 v76, s0, v117
	v_add_u32_e32 v92, 0x600, v202
	v_add_co_u32_e32 v72, vcc, s6, v72
	v_mad_i64_i32 v[76:77], s[8:9], v76, s5, v[160:161]
	v_ashrrev_i32_e32 v118, 6, v92
	v_addc_co_u32_e32 v73, vcc, 0, v73, vcc
	v_lshl_add_u64 v[76:77], v[76:77], 0, v[166:167]
	v_add_u32_e32 v92, s0, v118
	v_add_u32_e32 v96, 0x800, v202
	v_add_co_u32_e32 v76, vcc, s6, v76
	v_mad_i64_i32 v[92:93], s[8:9], v92, s5, v[160:161]
	v_ashrrev_i32_e32 v119, 6, v96
	v_addc_co_u32_e32 v77, vcc, 0, v77, vcc
	v_lshl_add_u64 v[92:93], v[92:93], 0, v[166:167]
	v_add_u32_e32 v96, s0, v119
	v_add_u32_e32 v100, 0xa00, v202
	v_add_co_u32_e32 v92, vcc, s6, v92
	v_mad_i64_i32 v[96:97], s[8:9], v96, s5, v[160:161]
	v_ashrrev_i32_e32 v120, 6, v100
	v_addc_co_u32_e32 v93, vcc, 0, v93, vcc
	v_lshl_add_u64 v[96:97], v[96:97], 0, v[166:167]
	v_add_u32_e32 v100, s0, v120
	v_add_u32_e32 v104, 0xc00, v202
	v_add_co_u32_e32 v96, vcc, s6, v96
	v_mad_i64_i32 v[100:101], s[8:9], v100, s5, v[160:161]
	v_ashrrev_i32_e32 v121, 6, v104
	global_load_dwordx4 v[68:71], v[68:69], off
	v_addc_co_u32_e32 v97, vcc, 0, v97, vcc
	v_lshl_add_u64 v[100:101], v[100:101], 0, v[166:167]
	v_add_u32_e32 v104, s0, v121
	v_add_u32_e32 v108, 0xe00, v202
	global_load_dwordx4 v[72:75], v[72:73], off
	v_add_co_u32_e32 v100, vcc, s6, v100
	v_mad_i64_i32 v[104:105], s[8:9], v104, s5, v[160:161]
	v_ashrrev_i32_e32 v122, 6, v108
	global_load_dwordx4 v[76:79], v[76:77], off
	v_addc_co_u32_e32 v101, vcc, 0, v101, vcc
; #define LAS __attribute__((address_space(3)))
; DI int crow(int r, int hi) { return (r & 3) + 8 * (r >> 2) + 4 * hi; }
; DI void stage_vT(const bf16_t* proj, int tok0, LAS unsigned char* lds, int tid) {
;     ...
;     for (int i8 = 0; i8 < 8; ++i8) { const int piece = tid + 512 * i8, row = piece >> 6, cp = piece & 63; w[i8] = *(const u32x4*)(proj + (size_t)(tok0 + row) * NPROJ + C_GV + cp * 8); }
; #pragma unroll
;     for (int i8 = 0; i8 < 8; ++i8) { const int piece = tid + 512 * i8, row = piece >> 6, cp = piece & 63; *(LAS u32x4*)(vS + row * VS_PITCH + cp * 8) = w[i8]; }
; DI void gla_out_unit(int chunk, const Params& p, LAS unsigned char* lds) {
;     ...
;     f32x16 oT[4];
; #pragma unroll
;     for (int vb = 0; vb < 4; ++vb)
; #pragma unroll
;         for (int e = 0; e < 16; ++e) oT[vb][e] = 0.f;
; #pragma unroll
;     for (int vb = 0; vb < 4; ++vb)
; #pragma unroll
;         for (int ks = 0; ks < 4; ++ks) oT[vb] = __builtin_amdgcn_mfma_f32_32x32x16_bf16(sf[vb][ks], qf[ks], oT[vb], 0, 0, 0);
; #pragma unroll
;     for (int sb = 0; sb < 2; ++sb) {
;         if (sb <= cb) {
;         f32x16 X;
; #pragma unroll
;         for (int e = 0; e < 16; ++e) X[e] = 0.f;
; #pragma unroll
;         for (int ks = 0; ks < 4; ++ks) X = __builtin_amdgcn_mfma_f32_32x32x16_bf16(kf[sb][ks], qf[ks], X, 0, 0, 0);
;         if (sb == cb) {
; #pragma unroll
;             for (int i = 0; i < 16; ++i) if (crow(i, hi) > r32) X[i] = 0.f; }
	v_lshl_add_u64 v[104:105], v[104:105], 0, v[166:167]
	v_add_u32_e32 v108, s0, v122
	global_load_dwordx4 v[92:95], v[92:93], off
	v_add_co_u32_e32 v104, vcc, s6, v104
	v_mad_i64_i32 v[108:109], s[8:9], v108, s5, v[160:161]
	global_load_dwordx4 v[96:99], v[96:97], off
	v_addc_co_u32_e32 v105, vcc, 0, v105, vcc
	v_lshl_add_u64 v[108:109], v[108:109], 0, v[166:167]
	global_load_dwordx4 v[100:103], v[100:101], off
	v_add_co_u32_e32 v108, vcc, s6, v108
	global_load_dwordx4 v[104:107], v[104:105], off
	s_nop 0
	v_addc_co_u32_e32 v109, vcc, 0, v109, vcc
	global_load_dwordx4 v[108:111], v[108:109], off
	global_load_dwordx2 v[200:201], v[224:225], off offset:1024
	global_load_dwordx2 v[196:197], v[226:227], off offset:16
	global_load_dwordx2 v[194:195], v[226:227], off offset:32
	global_load_dwordx2 v[192:193], v[226:227], off offset:48
	global_load_dwordx2 v[190:191], v[226:227], off offset:64
	global_load_dwordx2 v[188:189], v[226:227], off offset:80
	global_load_dwordx2 v[186:187], v[226:227], off offset:96
	global_load_dwordx2 v[184:185], v[226:227], off offset:112
	global_load_dwordx2 v[182:183], v[226:227], off offset:128
	global_load_dwordx2 v[180:181], v[226:227], off offset:144
	global_load_dwordx2 v[178:179], v[226:227], off offset:160
	global_load_dwordx2 v[176:177], v[226:227], off offset:176
	global_load_dwordx2 v[174:175], v[226:227], off offset:192
	global_load_dwordx2 v[172:173], v[226:227], off offset:208
	global_load_dwordx2 v[170:171], v[226:227], off offset:224
	global_load_dwordx2 v[168:169], v[226:227], off offset:240
	v_add_u32_e32 v112, 0, v166
	v_mad_u64_u32 v[114:115], s[8:9], v113, s7, v[112:113]
	s_bitcmp1_b32 s13, 6
	s_cselect_b64 s[20:21], -1, 0
	s_and_b64 vcc, exec, s[20:21]
	v_cmp_le_u32_e64 s[40:41], v203, v199
	v_cmp_lt_u32_e64 s[42:43], v203, v199
	v_or_b32_e32 v222, 2, v203
	v_or_b32_e32 v221, 3, v203
	v_or_b32_e32 v166, 8, v203
	v_or_b32_e32 v220, 9, v203
	v_or_b32_e32 v219, 10, v203
	v_or_b32_e32 v218, 11, v203
	v_or_b32_e32 v205, 16, v203
	v_or_b32_e32 v217, 17, v203
	v_or_b32_e32 v216, 18, v203
	v_or_b32_e32 v215, 19, v203
	v_or_b32_e32 v207, 24, v203
	v_or_b32_e32 v214, 25, v203
	v_or_b32_e32 v213, 26, v203
	v_or_b32_e32 v212, 27, v203
	s_waitcnt vmcnt(23)
	ds_write_b128 v114, v[68:71]
	v_mad_u64_u32 v[68:69], s[8:9], v116, s7, v[112:113]
	s_waitcnt vmcnt(22)
	ds_write_b128 v68, v[72:75]
	v_mad_u64_u32 v[68:69], s[8:9], v117, s7, v[112:113]
	s_waitcnt vmcnt(21)
	ds_write_b128 v68, v[76:79]
	v_mad_u64_u32 v[68:69], s[8:9], v118, s7, v[112:113]
	s_waitcnt vmcnt(20)
	ds_write_b128 v68, v[92:95]
	v_mad_u64_u32 v[68:69], s[8:9], v119, s7, v[112:113]
	s_waitcnt vmcnt(19)
	ds_write_b128 v68, v[96:99]
	v_mad_u64_u32 v[68:69], s[8:9], v120, s7, v[112:113]
	s_waitcnt vmcnt(18)
	ds_write_b128 v68, v[100:103]
	v_mad_u64_u32 v[68:69], s[8:9], v121, s7, v[112:113]
	s_waitcnt vmcnt(17)
	ds_write_b128 v68, v[104:107]
	v_mad_u64_u32 v[68:69], s[8:9], v122, s7, v[112:113]
	s_waitcnt vmcnt(16)
	ds_write_b128 v68, v[108:111]
	v_mfma_f32_32x32x16_bf16 v[64:79], v[64:67], v[140:143], 0
	s_waitcnt lgkmcnt(0)
	s_barrier
	v_mfma_f32_32x32x16_bf16 v[112:127], v[28:31], v[140:143], 0
	v_mfma_f32_32x32x16_bf16 v[64:79], v[88:91], v[136:139], v[64:79]
	v_mfma_f32_32x32x16_bf16 v[112:127], v[12:15], v[136:139], v[112:127]
	v_mfma_f32_32x32x16_bf16 v[64:79], v[84:87], v[132:135], v[64:79]
	v_mfma_f32_32x32x16_bf16 v[112:127], v[8:11], v[132:135], v[112:127]
	v_mfma_f32_32x32x16_bf16 v[64:79], v[80:83], v[128:131], v[64:79]
	v_mfma_f32_32x32x16_bf16 v[80:95], v[60:63], v[140:143], 0
	v_mfma_f32_32x32x16_bf16 v[96:111], v[44:47], v[140:143], 0
	v_mfma_f32_32x32x16_bf16 v[112:127], v[4:7], v[128:131], v[112:127]
	v_mfma_f32_32x32x16_bf16 v[0:15], v[0:3], v[140:143], 0
	v_mfma_f32_32x32x16_bf16 v[80:95], v[56:59], v[136:139], v[80:95]
	v_mfma_f32_32x32x16_bf16 v[96:111], v[40:43], v[136:139], v[96:111]
	v_mfma_f32_32x32x16_bf16 v[0:15], v[24:27], v[136:139], v[0:15]
	v_mfma_f32_32x32x16_bf16 v[80:95], v[52:55], v[132:135], v[80:95]
	v_mfma_f32_32x32x16_bf16 v[96:111], v[36:39], v[132:135], v[96:111]
	v_mfma_f32_32x32x16_bf16 v[0:15], v[20:23], v[132:135], v[0:15]
	v_mfma_f32_32x32x16_bf16 v[80:95], v[48:51], v[128:131], v[80:95]
	v_mfma_f32_32x32x16_bf16 v[96:111], v[32:35], v[128:131], v[96:111]
	v_mfma_f32_32x32x16_bf16 v[0:15], v[16:19], v[128:131], v[0:15]
	s_cbranch_vccnz .LBB0_620
	v_cmp_le_u32_e32 vcc, v222, v199
	v_or_b32_e32 v16, 8, v203
	s_nop 8
	v_cndmask_b32_e64 v1, 0, v1, s[42:43]
	v_cndmask_b32_e32 v2, 0, v2, vcc
	v_cmp_le_u32_e32 vcc, v221, v199
	v_cndmask_b32_e64 v0, 0, v0, s[40:41]
	s_nop 0
	v_cndmask_b32_e32 v3, 0, v3, vcc
	v_cmp_le_u32_e32 vcc, v16, v199
	v_or_b32_e32 v16, 16, v203
	s_nop 0
	v_cndmask_b32_e32 v4, 0, v4, vcc
	v_cmp_le_u32_e32 vcc, v220, v199
	s_nop 1
	v_cndmask_b32_e32 v5, 0, v5, vcc
	v_cmp_le_u32_e32 vcc, v219, v199
	s_nop 1
	v_cndmask_b32_e32 v6, 0, v6, vcc
	v_cmp_le_u32_e32 vcc, v218, v199
	s_nop 1
	v_cndmask_b32_e32 v7, 0, v7, vcc
	v_cmp_le_u32_e32 vcc, v16, v199
	v_or_b32_e32 v16, 24, v203
	s_nop 0
	v_cndmask_b32_e32 v8, 0, v8, vcc
	v_cmp_le_u32_e32 vcc, v217, v199
	s_nop 1
	v_cndmask_b32_e32 v9, 0, v9, vcc
	v_cmp_le_u32_e32 vcc, v216, v199
	s_nop 1
	v_cndmask_b32_e32 v10, 0, v10, vcc
	v_cmp_le_u32_e32 vcc, v215, v199
	s_nop 1
	v_cndmask_b32_e32 v11, 0, v11, vcc
	v_cmp_le_u32_e32 vcc, v16, v199
	s_nop 1
	v_cndmask_b32_e32 v12, 0, v12, vcc
	v_cmp_le_u32_e32 vcc, v214, v199
	s_nop 1
	v_cndmask_b32_e32 v13, 0, v13, vcc
	v_cmp_le_u32_e32 vcc, v213, v199
	s_nop 1
	v_cndmask_b32_e32 v14, 0, v14, vcc
	v_cmp_le_u32_e32 vcc, v212, v199
	s_nop 1
	v_cndmask_b32_e32 v15, 0, v15, vcc
